# GEMM K-loop headers aligned to 64 bytes (s_nop fill) on top of the no-flip loops
# speedup vs baseline: 1.0077x; 1.0077x over previous
.LBB0_149:
	v_mov_b32_e32 v129, 0
	s_andn2_b64 vcc, exec, s[4:5]
	v_mov_b32_e32 v128, v129
	s_waitcnt vmcnt(0)
	v_mov_b32_e32 v127, v129
	v_mov_b32_e32 v126, v129
	v_mov_b32_e32 v125, v129
	v_mov_b32_e32 v124, v129
	v_mov_b32_e32 v123, v129
	v_mov_b32_e32 v122, v129
	v_mov_b32_e32 v113, v129
	v_mov_b32_e32 v112, v129
	v_mov_b32_e32 v111, v129
	v_mov_b32_e32 v110, v129
	v_mov_b32_e32 v109, v129
	v_mov_b32_e32 v108, v129
	v_mov_b32_e32 v107, v129
	v_mov_b32_e32 v106, v129
	v_mov_b32_e32 v97, v129
	v_mov_b32_e32 v96, v129
	v_mov_b32_e32 v95, v129
	v_mov_b32_e32 v94, v129
	v_mov_b32_e32 v93, v129
	v_mov_b32_e32 v92, v129
	v_mov_b32_e32 v91, v129
	v_mov_b32_e32 v90, v129
	v_mov_b32_e32 v81, v129
	v_mov_b32_e32 v80, v129
	v_mov_b32_e32 v79, v129
	v_mov_b32_e32 v78, v129
	v_mov_b32_e32 v77, v129
	v_mov_b32_e32 v76, v129
	v_mov_b32_e32 v75, v129
	v_mov_b32_e32 v74, v129
	v_mov_b32_e32 v121, v129
	v_mov_b32_e32 v120, v129
	v_mov_b32_e32 v119, v129
	v_mov_b32_e32 v118, v129
	v_mov_b32_e32 v117, v129
	v_mov_b32_e32 v116, v129
	v_mov_b32_e32 v115, v129
	v_mov_b32_e32 v114, v129
	v_mov_b32_e32 v105, v129
	v_mov_b32_e32 v104, v129
	v_mov_b32_e32 v103, v129
	v_mov_b32_e32 v102, v129
	v_mov_b32_e32 v101, v129
	v_mov_b32_e32 v100, v129
	v_mov_b32_e32 v99, v129
	v_mov_b32_e32 v98, v129
	v_mov_b32_e32 v89, v129
	v_mov_b32_e32 v88, v129
	v_mov_b32_e32 v87, v129
	v_mov_b32_e32 v86, v129
	v_mov_b32_e32 v85, v129
	v_mov_b32_e32 v84, v129
	v_mov_b32_e32 v83, v129
	v_mov_b32_e32 v82, v129
	v_mov_b32_e32 v73, v129
	v_mov_b32_e32 v72, v129
	v_mov_b32_e32 v71, v129
	v_mov_b32_e32 v70, v129
	v_mov_b32_e32 v69, v129
	v_mov_b32_e32 v68, v129
	v_mov_b32_e32 v67, v129
	v_mov_b32_e32 v66, v129
	v_mov_b32_e32 v65, v129
	v_mov_b32_e32 v64, v129
	v_mov_b32_e32 v63, v129
	v_mov_b32_e32 v62, v129
	v_mov_b32_e32 v61, v129
	v_mov_b32_e32 v60, v129
	v_mov_b32_e32 v59, v129
	v_mov_b32_e32 v58, v129
	v_mov_b32_e32 v49, v129
	v_mov_b32_e32 v48, v129
	v_mov_b32_e32 v47, v129
	v_mov_b32_e32 v46, v129
	v_mov_b32_e32 v45, v129
	v_mov_b32_e32 v44, v129
	v_mov_b32_e32 v43, v129
	v_mov_b32_e32 v42, v129
	v_mov_b32_e32 v33, v129
	v_mov_b32_e32 v32, v129
	v_mov_b32_e32 v31, v129
	v_mov_b32_e32 v30, v129
	v_mov_b32_e32 v29, v129
	v_mov_b32_e32 v28, v129
	v_mov_b32_e32 v27, v129
	v_mov_b32_e32 v26, v129
	v_mov_b32_e32 v17, v129
	v_mov_b32_e32 v16, v129
	v_mov_b32_e32 v15, v129
	v_mov_b32_e32 v14, v129
	v_mov_b32_e32 v13, v129
	v_mov_b32_e32 v12, v129
	v_mov_b32_e32 v11, v129
	v_mov_b32_e32 v10, v129
	v_mov_b32_e32 v57, v129
	v_mov_b32_e32 v56, v129
	v_mov_b32_e32 v55, v129
	v_mov_b32_e32 v54, v129
	v_mov_b32_e32 v53, v129
	v_mov_b32_e32 v52, v129
	v_mov_b32_e32 v51, v129
	v_mov_b32_e32 v50, v129
	v_mov_b32_e32 v41, v129
	v_mov_b32_e32 v40, v129
	v_mov_b32_e32 v39, v129
	v_mov_b32_e32 v38, v129
	v_mov_b32_e32 v37, v129
	v_mov_b32_e32 v36, v129
	v_mov_b32_e32 v35, v129
	v_mov_b32_e32 v34, v129
	v_mov_b32_e32 v25, v129
	v_mov_b32_e32 v24, v129
	v_mov_b32_e32 v23, v129
	v_mov_b32_e32 v22, v129
	v_mov_b32_e32 v21, v129
	v_mov_b32_e32 v20, v129
	v_mov_b32_e32 v19, v129
	v_mov_b32_e32 v18, v129
	v_mov_b32_e32 v9, v129
	v_mov_b32_e32 v8, v129
	v_mov_b32_e32 v7, v129
	v_mov_b32_e32 v6, v129
	v_mov_b32_e32 v5, v129
	v_mov_b32_e32 v4, v129
	v_mov_b32_e32 v3, v129
	v_mov_b32_e32 v2, v129
	s_cbranch_vccnz .LBB0_138
	s_add_u32 s41, s6, 0x100
	s_addc_u32 s42, s7, 0
	s_add_u32 s6, s8, 0xc000
	v_mov_b32_e32 v2, 0
	s_addc_u32 s7, s9, 0
	s_mov_b32 s8, 0
	v_mov_b32_e32 v3, v2
	v_mov_b32_e32 v4, v2
	v_mov_b32_e32 v5, v2
	v_mov_b32_e32 v6, v2
	v_mov_b32_e32 v7, v2
	v_mov_b32_e32 v8, v2
	v_mov_b32_e32 v9, v2
	v_mov_b32_e32 v18, v2
	v_mov_b32_e32 v19, v2
	v_mov_b32_e32 v20, v2
	v_mov_b32_e32 v21, v2
	v_mov_b32_e32 v22, v2
	v_mov_b32_e32 v23, v2
	v_mov_b32_e32 v24, v2
	v_mov_b32_e32 v25, v2
	v_mov_b32_e32 v34, v2
	v_mov_b32_e32 v35, v2
	v_mov_b32_e32 v36, v2
	v_mov_b32_e32 v37, v2
	v_mov_b32_e32 v38, v2
	v_mov_b32_e32 v39, v2
	v_mov_b32_e32 v40, v2
	v_mov_b32_e32 v41, v2
	v_mov_b32_e32 v50, v2
	v_mov_b32_e32 v51, v2
	v_mov_b32_e32 v52, v2
	v_mov_b32_e32 v53, v2
	v_mov_b32_e32 v54, v2
	v_mov_b32_e32 v55, v2
	v_mov_b32_e32 v56, v2
	v_mov_b32_e32 v57, v2
	v_mov_b32_e32 v10, v2
	v_mov_b32_e32 v11, v2
	v_mov_b32_e32 v12, v2
	v_mov_b32_e32 v13, v2
	v_mov_b32_e32 v14, v2
	v_mov_b32_e32 v15, v2
	v_mov_b32_e32 v16, v2
	v_mov_b32_e32 v17, v2
	v_mov_b32_e32 v26, v2
	v_mov_b32_e32 v27, v2
	v_mov_b32_e32 v28, v2
	v_mov_b32_e32 v29, v2
	v_mov_b32_e32 v30, v2
	v_mov_b32_e32 v31, v2
	v_mov_b32_e32 v32, v2
	v_mov_b32_e32 v33, v2
	v_mov_b32_e32 v42, v2
	v_mov_b32_e32 v43, v2
	v_mov_b32_e32 v44, v2
	v_mov_b32_e32 v45, v2
	v_mov_b32_e32 v46, v2
	v_mov_b32_e32 v47, v2
	v_mov_b32_e32 v48, v2
	v_mov_b32_e32 v49, v2
	v_mov_b32_e32 v58, v2
	v_mov_b32_e32 v59, v2
	v_mov_b32_e32 v60, v2
	v_mov_b32_e32 v61, v2
	v_mov_b32_e32 v62, v2
	v_mov_b32_e32 v63, v2
	v_mov_b32_e32 v64, v2
	v_mov_b32_e32 v65, v2
	v_mov_b32_e32 v66, v2
	v_mov_b32_e32 v67, v2
	v_mov_b32_e32 v68, v2
	v_mov_b32_e32 v69, v2
	v_mov_b32_e32 v70, v2
	v_mov_b32_e32 v71, v2
	v_mov_b32_e32 v72, v2
	v_mov_b32_e32 v73, v2
	v_mov_b32_e32 v82, v2
	v_mov_b32_e32 v83, v2
	v_mov_b32_e32 v84, v2
	v_mov_b32_e32 v85, v2
	v_mov_b32_e32 v86, v2
	v_mov_b32_e32 v87, v2
	v_mov_b32_e32 v88, v2
	v_mov_b32_e32 v89, v2
	v_mov_b32_e32 v98, v2
	v_mov_b32_e32 v99, v2
	v_mov_b32_e32 v100, v2
	v_mov_b32_e32 v101, v2
	v_mov_b32_e32 v102, v2
	v_mov_b32_e32 v103, v2
	v_mov_b32_e32 v104, v2
	v_mov_b32_e32 v105, v2
	v_mov_b32_e32 v114, v2
	v_mov_b32_e32 v115, v2
	v_mov_b32_e32 v116, v2
	v_mov_b32_e32 v117, v2
	v_mov_b32_e32 v118, v2
	v_mov_b32_e32 v119, v2
	v_mov_b32_e32 v120, v2
	v_mov_b32_e32 v121, v2
	v_mov_b32_e32 v74, v2
	v_mov_b32_e32 v75, v2
	v_mov_b32_e32 v76, v2
	v_mov_b32_e32 v77, v2
	v_mov_b32_e32 v78, v2
	v_mov_b32_e32 v79, v2
	v_mov_b32_e32 v80, v2
	v_mov_b32_e32 v81, v2
	v_mov_b32_e32 v90, v2
	v_mov_b32_e32 v91, v2
	v_mov_b32_e32 v92, v2
	v_mov_b32_e32 v93, v2
	v_mov_b32_e32 v94, v2
	v_mov_b32_e32 v95, v2
	v_mov_b32_e32 v96, v2
	v_mov_b32_e32 v97, v2
	v_mov_b32_e32 v106, v2
	v_mov_b32_e32 v107, v2
	v_mov_b32_e32 v108, v2
	v_mov_b32_e32 v109, v2
	v_mov_b32_e32 v110, v2
	v_mov_b32_e32 v111, v2
	v_mov_b32_e32 v112, v2
	v_mov_b32_e32 v113, v2
	v_mov_b32_e32 v122, v2
	v_mov_b32_e32 v123, v2
	v_mov_b32_e32 v124, v2
	v_mov_b32_e32 v125, v2
	v_mov_b32_e32 v126, v2
	v_mov_b32_e32 v127, v2
	v_mov_b32_e32 v128, v2
	v_mov_b32_e32 v129, v2
	.p2alignl 6, 3212836864

.LBB0_164:
	s_ashr_i32 s7, s6, 31
	s_lshl_b64 s[8:9], s[6:7], 19
	s_add_u32 s8, s64, s8
	s_addc_u32 s9, s65, s9
	s_ashr_i32 s5, s4, 31
	s_lshl_b64 s[10:11], s[4:5], 19
	s_add_u32 s10, s21, s10
	v_mov_b32_e32 v141, 0
	s_addc_u32 s11, s22, s11
	s_andn2_b64 vcc, exec, s[2:3]
	v_mov_b32_e32 v140, v141
	v_mov_b32_e32 v139, v141
	v_mov_b32_e32 v138, v141
	v_mov_b32_e32 v137, v141
	v_mov_b32_e32 v136, v141
	v_mov_b32_e32 v135, v141
	v_mov_b32_e32 v134, v141
	v_mov_b32_e32 v129, v141
	v_mov_b32_e32 v128, v141
	s_waitcnt vmcnt(0)
	v_mov_b32_e32 v127, v141
	v_mov_b32_e32 v126, v141
	v_mov_b32_e32 v121, v141
	v_mov_b32_e32 v120, v141
	v_mov_b32_e32 v119, v141
	v_mov_b32_e32 v118, v141
	v_mov_b32_e32 v113, v141
	v_mov_b32_e32 v112, v141
	v_mov_b32_e32 v111, v141
	v_mov_b32_e32 v110, v141
	v_mov_b32_e32 v97, v141
	v_mov_b32_e32 v96, v141
	v_mov_b32_e32 v95, v141
	v_mov_b32_e32 v94, v141
	v_mov_b32_e32 v81, v141
	v_mov_b32_e32 v80, v141
	v_mov_b32_e32 v79, v141
	v_mov_b32_e32 v78, v141
	v_mov_b32_e32 v73, v141
	v_mov_b32_e32 v72, v141
	v_mov_b32_e32 v71, v141
	v_mov_b32_e32 v70, v141
	v_mov_b32_e32 v145, v141
	v_mov_b32_e32 v144, v141
	v_mov_b32_e32 v143, v141
	v_mov_b32_e32 v142, v141
	v_mov_b32_e32 v133, v141
	v_mov_b32_e32 v132, v141
	v_mov_b32_e32 v131, v141
	v_mov_b32_e32 v130, v141
	v_mov_b32_e32 v125, v141
	v_mov_b32_e32 v124, v141
	v_mov_b32_e32 v123, v141
	v_mov_b32_e32 v122, v141
	v_mov_b32_e32 v117, v141
	v_mov_b32_e32 v116, v141
	v_mov_b32_e32 v115, v141
	v_mov_b32_e32 v114, v141
	v_mov_b32_e32 v109, v141
	v_mov_b32_e32 v108, v141
	v_mov_b32_e32 v107, v141
	v_mov_b32_e32 v106, v141
	v_mov_b32_e32 v93, v141
	v_mov_b32_e32 v92, v141
	v_mov_b32_e32 v91, v141
	v_mov_b32_e32 v90, v141
	v_mov_b32_e32 v77, v141
	v_mov_b32_e32 v76, v141
	v_mov_b32_e32 v75, v141
	v_mov_b32_e32 v74, v141
	v_mov_b32_e32 v69, v141
	v_mov_b32_e32 v68, v141
	v_mov_b32_e32 v67, v141
	v_mov_b32_e32 v66, v141
	v_mov_b32_e32 v65, v141
	v_mov_b32_e32 v64, v141
	v_mov_b32_e32 v63, v141
	v_mov_b32_e32 v62, v141
	v_mov_b32_e32 v57, v141
	v_mov_b32_e32 v56, v141
	v_mov_b32_e32 v55, v141
	v_mov_b32_e32 v54, v141
	v_mov_b32_e32 v49, v141
	v_mov_b32_e32 v48, v141
	v_mov_b32_e32 v47, v141
	v_mov_b32_e32 v46, v141
	v_mov_b32_e32 v41, v141
	v_mov_b32_e32 v40, v141
	v_mov_b32_e32 v39, v141
	v_mov_b32_e32 v38, v141
	v_mov_b32_e32 v33, v141
	v_mov_b32_e32 v32, v141
	v_mov_b32_e32 v31, v141
	v_mov_b32_e32 v30, v141
	v_mov_b32_e32 v25, v141
	v_mov_b32_e32 v24, v141
	v_mov_b32_e32 v23, v141
	v_mov_b32_e32 v22, v141
	v_mov_b32_e32 v17, v141
	v_mov_b32_e32 v16, v141
	v_mov_b32_e32 v15, v141
	v_mov_b32_e32 v14, v141
	v_mov_b32_e32 v9, v141
	v_mov_b32_e32 v8, v141
	v_mov_b32_e32 v7, v141
	v_mov_b32_e32 v6, v141
	v_mov_b32_e32 v61, v141
	v_mov_b32_e32 v60, v141
	v_mov_b32_e32 v59, v141
	v_mov_b32_e32 v58, v141
	v_mov_b32_e32 v53, v141
	v_mov_b32_e32 v52, v141
	v_mov_b32_e32 v51, v141
	v_mov_b32_e32 v50, v141
	v_mov_b32_e32 v45, v141
	v_mov_b32_e32 v44, v141
	v_mov_b32_e32 v43, v141
	v_mov_b32_e32 v42, v141
	v_mov_b32_e32 v37, v141
	v_mov_b32_e32 v36, v141
	v_mov_b32_e32 v35, v141
	v_mov_b32_e32 v34, v141
	v_mov_b32_e32 v29, v141
	v_mov_b32_e32 v28, v141
	v_mov_b32_e32 v27, v141
	v_mov_b32_e32 v26, v141
	v_mov_b32_e32 v21, v141
	v_mov_b32_e32 v20, v141
	v_mov_b32_e32 v19, v141
	v_mov_b32_e32 v18, v141
	v_mov_b32_e32 v13, v141
	v_mov_b32_e32 v12, v141
	v_mov_b32_e32 v11, v141
	v_mov_b32_e32 v10, v141
	v_mov_b32_e32 v5, v141
	v_mov_b32_e32 v4, v141
	v_mov_b32_e32 v3, v141
	v_mov_b32_e32 v2, v141
	s_cbranch_vccnz .LBB0_161
	v_mov_b64_e32 v[2:3], 0xb00
	v_cmp_lt_i64_e32 vcc, s[18:19], v[2:3]
	s_and_b64 s[18:19], vcc, exec
	s_cselect_b32 s5, s9, s15
	s_cselect_b32 s7, s8, s14
	s_cselect_b32 s43, s11, s17
	s_cselect_b32 s44, s10, s16
	s_add_u32 s14, s14, 0x40080
	s_addc_u32 s15, s15, 0
	s_add_u32 s45, s16, 0x100
	v_mov_b32_e32 v2, 0
	s_addc_u32 s46, s17, 0
	s_mov_b32 s16, 0
	v_mov_b32_e32 v3, v2
	v_mov_b32_e32 v4, v2
	v_mov_b32_e32 v5, v2
	v_mov_b32_e32 v10, v2
	v_mov_b32_e32 v11, v2
	v_mov_b32_e32 v12, v2
	v_mov_b32_e32 v13, v2
	v_mov_b32_e32 v18, v2
	v_mov_b32_e32 v19, v2
	v_mov_b32_e32 v20, v2
	v_mov_b32_e32 v21, v2
	v_mov_b32_e32 v26, v2
	v_mov_b32_e32 v27, v2
	v_mov_b32_e32 v28, v2
	v_mov_b32_e32 v29, v2
	v_mov_b32_e32 v34, v2
	v_mov_b32_e32 v35, v2
	v_mov_b32_e32 v36, v2
	v_mov_b32_e32 v37, v2
	v_mov_b32_e32 v42, v2
	v_mov_b32_e32 v43, v2
	v_mov_b32_e32 v44, v2
	v_mov_b32_e32 v45, v2
	v_mov_b32_e32 v50, v2
	v_mov_b32_e32 v51, v2
	v_mov_b32_e32 v52, v2
	v_mov_b32_e32 v53, v2
	v_mov_b32_e32 v58, v2
	v_mov_b32_e32 v59, v2
	v_mov_b32_e32 v60, v2
	v_mov_b32_e32 v61, v2
	v_mov_b32_e32 v6, v2
	v_mov_b32_e32 v7, v2
	v_mov_b32_e32 v8, v2
	v_mov_b32_e32 v9, v2
	v_mov_b32_e32 v14, v2
	v_mov_b32_e32 v15, v2
	v_mov_b32_e32 v16, v2
	v_mov_b32_e32 v17, v2
	v_mov_b32_e32 v22, v2
	v_mov_b32_e32 v23, v2
	v_mov_b32_e32 v24, v2
	v_mov_b32_e32 v25, v2
	v_mov_b32_e32 v30, v2
	v_mov_b32_e32 v31, v2
	v_mov_b32_e32 v32, v2
	v_mov_b32_e32 v33, v2
	v_mov_b32_e32 v38, v2
	v_mov_b32_e32 v39, v2
	v_mov_b32_e32 v40, v2
	v_mov_b32_e32 v41, v2
	v_mov_b32_e32 v46, v2
	v_mov_b32_e32 v47, v2
	v_mov_b32_e32 v48, v2
	v_mov_b32_e32 v49, v2
	v_mov_b32_e32 v54, v2
	v_mov_b32_e32 v55, v2
	v_mov_b32_e32 v56, v2
	v_mov_b32_e32 v57, v2
	v_mov_b32_e32 v62, v2
	v_mov_b32_e32 v63, v2
	v_mov_b32_e32 v64, v2
	v_mov_b32_e32 v65, v2
	v_mov_b32_e32 v66, v2
	v_mov_b32_e32 v67, v2
	v_mov_b32_e32 v68, v2
	v_mov_b32_e32 v69, v2
	v_mov_b32_e32 v74, v2
	v_mov_b32_e32 v75, v2
	v_mov_b32_e32 v76, v2
	v_mov_b32_e32 v77, v2
	v_mov_b32_e32 v90, v2
	v_mov_b32_e32 v91, v2
	v_mov_b32_e32 v92, v2
	v_mov_b32_e32 v93, v2
	v_mov_b32_e32 v106, v2
	v_mov_b32_e32 v107, v2
	v_mov_b32_e32 v108, v2
	v_mov_b32_e32 v109, v2
	v_mov_b32_e32 v114, v2
	v_mov_b32_e32 v115, v2
	v_mov_b32_e32 v116, v2
	v_mov_b32_e32 v117, v2
	v_mov_b32_e32 v122, v2
	v_mov_b32_e32 v123, v2
	v_mov_b32_e32 v124, v2
	v_mov_b32_e32 v125, v2
	v_mov_b32_e32 v130, v2
	v_mov_b32_e32 v131, v2
	v_mov_b32_e32 v132, v2
	v_mov_b32_e32 v133, v2
	v_mov_b32_e32 v142, v2
	v_mov_b32_e32 v143, v2
	v_mov_b32_e32 v144, v2
	v_mov_b32_e32 v145, v2
	v_mov_b32_e32 v70, v2
	v_mov_b32_e32 v71, v2
	v_mov_b32_e32 v72, v2
	v_mov_b32_e32 v73, v2
	v_mov_b32_e32 v78, v2
	v_mov_b32_e32 v79, v2
	v_mov_b32_e32 v80, v2
	v_mov_b32_e32 v81, v2
	v_mov_b32_e32 v94, v2
	v_mov_b32_e32 v95, v2
	v_mov_b32_e32 v96, v2
	v_mov_b32_e32 v97, v2
	v_mov_b32_e32 v110, v2
	v_mov_b32_e32 v111, v2
	v_mov_b32_e32 v112, v2
	v_mov_b32_e32 v113, v2
	v_mov_b32_e32 v118, v2
	v_mov_b32_e32 v119, v2
	v_mov_b32_e32 v120, v2
	v_mov_b32_e32 v121, v2
	v_mov_b32_e32 v126, v2
	v_mov_b32_e32 v127, v2
	v_mov_b32_e32 v128, v2
	v_mov_b32_e32 v129, v2
	v_mov_b32_e32 v134, v2
	v_mov_b32_e32 v135, v2
	v_mov_b32_e32 v136, v2
	v_mov_b32_e32 v137, v2
	v_mov_b32_e32 v138, v2
	v_mov_b32_e32 v139, v2
	v_mov_b32_e32 v140, v2
	v_mov_b32_e32 v141, v2
	.p2alignl 6, 3212836864

.LBB0_189:
	s_ashr_i32 s9, s8, 31
	s_lshl_b64 s[10:11], s[8:9], 19
	s_add_u32 s10, s23, s10
	s_addc_u32 s11, s24, s11
	s_ashr_i32 s7, s6, 31
	s_lshl_b64 s[12:13], s[6:7], 19
	s_add_u32 s12, s25, s12
	v_mov_b32_e32 v145, 0
	v_cmp_lt_i64_e64 s[0:1], s[0:1], v[162:163]
	s_addc_u32 s13, s26, s13
	s_andn2_b64 vcc, exec, s[4:5]
	v_mov_b32_e32 v144, v145
	v_mov_b32_e32 v143, v145
	v_mov_b32_e32 v142, v145
	v_mov_b32_e32 v141, v145
	v_mov_b32_e32 v140, v145
	v_mov_b32_e32 v139, v145
	v_mov_b32_e32 v138, v145
	v_mov_b32_e32 v129, v145
	v_mov_b32_e32 v128, v145
	s_waitcnt vmcnt(0)
	v_mov_b32_e32 v127, v145
	v_mov_b32_e32 v126, v145
	v_mov_b32_e32 v121, v145
	v_mov_b32_e32 v120, v145
	v_mov_b32_e32 v119, v145
	v_mov_b32_e32 v118, v145
	v_mov_b32_e32 v101, v145
	v_mov_b32_e32 v100, v145
	v_mov_b32_e32 v99, v145
	v_mov_b32_e32 v98, v145
	v_mov_b32_e32 v97, v145
	v_mov_b32_e32 v96, v145
	v_mov_b32_e32 v95, v145
	v_mov_b32_e32 v94, v145
	v_mov_b32_e32 v81, v145
	v_mov_b32_e32 v80, v145
	v_mov_b32_e32 v79, v145
	v_mov_b32_e32 v78, v145
	v_mov_b32_e32 v77, v145
	v_mov_b32_e32 v76, v145
	v_mov_b32_e32 v75, v145
	v_mov_b32_e32 v74, v145
	v_mov_b32_e32 v137, v145
	v_mov_b32_e32 v136, v145
	v_mov_b32_e32 v135, v145
	v_mov_b32_e32 v134, v145
	v_mov_b32_e32 v133, v145
	v_mov_b32_e32 v132, v145
	v_mov_b32_e32 v131, v145
	v_mov_b32_e32 v130, v145
	v_mov_b32_e32 v117, v145
	v_mov_b32_e32 v116, v145
	v_mov_b32_e32 v115, v145
	v_mov_b32_e32 v114, v145
	v_mov_b32_e32 v109, v145
	v_mov_b32_e32 v108, v145
	v_mov_b32_e32 v107, v145
	v_mov_b32_e32 v106, v145
	v_mov_b32_e32 v89, v145
	v_mov_b32_e32 v88, v145
	v_mov_b32_e32 v87, v145
	v_mov_b32_e32 v86, v145
	v_mov_b32_e32 v85, v145
	v_mov_b32_e32 v84, v145
	v_mov_b32_e32 v83, v145
	v_mov_b32_e32 v82, v145
	v_mov_b32_e32 v73, v145
	v_mov_b32_e32 v72, v145
	v_mov_b32_e32 v71, v145
	v_mov_b32_e32 v70, v145
	v_mov_b32_e32 v69, v145
	v_mov_b32_e32 v68, v145
	v_mov_b32_e32 v67, v145
	v_mov_b32_e32 v66, v145
	v_mov_b32_e32 v65, v145
	v_mov_b32_e32 v64, v145
	v_mov_b32_e32 v63, v145
	v_mov_b32_e32 v62, v145
	v_mov_b32_e32 v61, v145
	v_mov_b32_e32 v60, v145
	v_mov_b32_e32 v59, v145
	v_mov_b32_e32 v58, v145
	v_mov_b32_e32 v49, v145
	v_mov_b32_e32 v48, v145
	v_mov_b32_e32 v47, v145
	v_mov_b32_e32 v46, v145
	v_mov_b32_e32 v45, v145
	v_mov_b32_e32 v44, v145
	v_mov_b32_e32 v43, v145
	v_mov_b32_e32 v42, v145
	v_mov_b32_e32 v33, v145
	v_mov_b32_e32 v32, v145
	v_mov_b32_e32 v31, v145
	v_mov_b32_e32 v30, v145
	v_mov_b32_e32 v29, v145
	v_mov_b32_e32 v28, v145
	v_mov_b32_e32 v27, v145
	v_mov_b32_e32 v26, v145
	v_mov_b32_e32 v17, v145
	v_mov_b32_e32 v16, v145
	v_mov_b32_e32 v15, v145
	v_mov_b32_e32 v14, v145
	v_mov_b32_e32 v13, v145
	v_mov_b32_e32 v12, v145
	v_mov_b32_e32 v11, v145
	v_mov_b32_e32 v10, v145
	v_mov_b32_e32 v57, v145
	v_mov_b32_e32 v56, v145
	v_mov_b32_e32 v55, v145
	v_mov_b32_e32 v54, v145
	v_mov_b32_e32 v53, v145
	v_mov_b32_e32 v52, v145
	v_mov_b32_e32 v51, v145
	v_mov_b32_e32 v50, v145
	v_mov_b32_e32 v41, v145
	v_mov_b32_e32 v40, v145
	v_mov_b32_e32 v39, v145
	v_mov_b32_e32 v38, v145
	v_mov_b32_e32 v37, v145
	v_mov_b32_e32 v36, v145
	v_mov_b32_e32 v35, v145
	v_mov_b32_e32 v34, v145
	v_mov_b32_e32 v25, v145
	v_mov_b32_e32 v24, v145
	v_mov_b32_e32 v23, v145
	v_mov_b32_e32 v22, v145
	v_mov_b32_e32 v21, v145
	v_mov_b32_e32 v20, v145
	v_mov_b32_e32 v19, v145
	v_mov_b32_e32 v18, v145
	v_mov_b32_e32 v9, v145
	v_mov_b32_e32 v8, v145
	v_mov_b32_e32 v7, v145
	v_mov_b32_e32 v6, v145
	v_mov_b32_e32 v5, v145
	v_mov_b32_e32 v4, v145
	s_waitcnt lgkmcnt(0)
	v_mov_b32_e32 v3, v145
	v_mov_b32_e32 v2, v145
	s_cbranch_vccnz .LBB0_192
	s_and_b64 s[0:1], s[0:1], exec
	s_cselect_b32 s7, s11, s21
	s_cselect_b32 s9, s10, s20
	s_cselect_b32 s47, s13, s19
	s_cselect_b32 s48, s12, s18
	s_add_u32 s49, s18, 0x100
	s_addc_u32 s50, s19, 0
	s_add_u32 s0, s20, 0x40080
	v_mov_b32_e32 v2, 0
	s_addc_u32 s1, s21, 0
	s_mov_b32 s18, 0
	v_mov_b32_e32 v3, v2
	v_mov_b32_e32 v4, v2
	v_mov_b32_e32 v5, v2
	v_mov_b32_e32 v6, v2
	v_mov_b32_e32 v7, v2
	v_mov_b32_e32 v8, v2
	v_mov_b32_e32 v9, v2
	v_mov_b32_e32 v18, v2
	v_mov_b32_e32 v19, v2
	v_mov_b32_e32 v20, v2
	v_mov_b32_e32 v21, v2
	v_mov_b32_e32 v22, v2
	v_mov_b32_e32 v23, v2
	v_mov_b32_e32 v24, v2
	v_mov_b32_e32 v25, v2
	v_mov_b32_e32 v34, v2
	v_mov_b32_e32 v35, v2
	v_mov_b32_e32 v36, v2
	v_mov_b32_e32 v37, v2
	v_mov_b32_e32 v38, v2
	v_mov_b32_e32 v39, v2
	v_mov_b32_e32 v40, v2
	v_mov_b32_e32 v41, v2
	v_mov_b32_e32 v50, v2
	v_mov_b32_e32 v51, v2
	v_mov_b32_e32 v52, v2
	v_mov_b32_e32 v53, v2
	v_mov_b32_e32 v54, v2
	v_mov_b32_e32 v55, v2
	v_mov_b32_e32 v56, v2
	v_mov_b32_e32 v57, v2
	v_mov_b32_e32 v10, v2
	v_mov_b32_e32 v11, v2
	v_mov_b32_e32 v12, v2
	v_mov_b32_e32 v13, v2
	v_mov_b32_e32 v14, v2
	v_mov_b32_e32 v15, v2
	v_mov_b32_e32 v16, v2
	v_mov_b32_e32 v17, v2
	v_mov_b32_e32 v26, v2
	v_mov_b32_e32 v27, v2
	v_mov_b32_e32 v28, v2
	v_mov_b32_e32 v29, v2
	v_mov_b32_e32 v30, v2
	v_mov_b32_e32 v31, v2
	v_mov_b32_e32 v32, v2
	v_mov_b32_e32 v33, v2
	v_mov_b32_e32 v42, v2
	v_mov_b32_e32 v43, v2
	v_mov_b32_e32 v44, v2
	v_mov_b32_e32 v45, v2
	v_mov_b32_e32 v46, v2
	v_mov_b32_e32 v47, v2
	v_mov_b32_e32 v48, v2
	v_mov_b32_e32 v49, v2
	v_mov_b32_e32 v58, v2
	v_mov_b32_e32 v59, v2
	v_mov_b32_e32 v60, v2
	v_mov_b32_e32 v61, v2
	v_mov_b32_e32 v62, v2
	v_mov_b32_e32 v63, v2
	v_mov_b32_e32 v64, v2
	v_mov_b32_e32 v65, v2
	v_mov_b32_e32 v66, v2
	v_mov_b32_e32 v67, v2
	v_mov_b32_e32 v68, v2
	v_mov_b32_e32 v69, v2
	v_mov_b32_e32 v70, v2
	v_mov_b32_e32 v71, v2
	v_mov_b32_e32 v72, v2
	v_mov_b32_e32 v73, v2
	v_mov_b32_e32 v82, v2
	v_mov_b32_e32 v83, v2
	v_mov_b32_e32 v84, v2
	v_mov_b32_e32 v85, v2
	v_mov_b32_e32 v86, v2
	v_mov_b32_e32 v87, v2
	v_mov_b32_e32 v88, v2
	v_mov_b32_e32 v89, v2
	v_mov_b32_e32 v106, v2
	v_mov_b32_e32 v107, v2
	v_mov_b32_e32 v108, v2
	v_mov_b32_e32 v109, v2
	v_mov_b32_e32 v114, v2
	v_mov_b32_e32 v115, v2
	v_mov_b32_e32 v116, v2
	v_mov_b32_e32 v117, v2
	v_mov_b32_e32 v130, v2
	v_mov_b32_e32 v131, v2
	v_mov_b32_e32 v132, v2
	v_mov_b32_e32 v133, v2
	v_mov_b32_e32 v134, v2
	v_mov_b32_e32 v135, v2
	v_mov_b32_e32 v136, v2
	v_mov_b32_e32 v137, v2
	v_mov_b32_e32 v74, v2
	v_mov_b32_e32 v75, v2
	v_mov_b32_e32 v76, v2
	v_mov_b32_e32 v77, v2
	v_mov_b32_e32 v78, v2
	v_mov_b32_e32 v79, v2
	v_mov_b32_e32 v80, v2
	v_mov_b32_e32 v81, v2
	v_mov_b32_e32 v94, v2
	v_mov_b32_e32 v95, v2
	v_mov_b32_e32 v96, v2
	v_mov_b32_e32 v97, v2
	v_mov_b32_e32 v98, v2
	v_mov_b32_e32 v99, v2
	v_mov_b32_e32 v100, v2
	v_mov_b32_e32 v101, v2
	v_mov_b32_e32 v118, v2
	v_mov_b32_e32 v119, v2
	v_mov_b32_e32 v120, v2
	v_mov_b32_e32 v121, v2
	v_mov_b32_e32 v126, v2
	v_mov_b32_e32 v127, v2
	v_mov_b32_e32 v128, v2
	v_mov_b32_e32 v129, v2
	v_mov_b32_e32 v138, v2
	v_mov_b32_e32 v139, v2
	v_mov_b32_e32 v140, v2
	v_mov_b32_e32 v141, v2
	v_mov_b32_e32 v142, v2
	v_mov_b32_e32 v143, v2
	v_mov_b32_e32 v144, v2
	v_mov_b32_e32 v145, v2
	.p2alignl 6, 3212836864

.LBB0_425:
	v_mov_b32_e32 v133, v0
	v_lshl_add_u64 v[2:3], s[0:1], 0, v[132:133]
	v_mov_b32_e32 v137, v0
	v_lshl_add_u64 v[4:5], s[0:1], 0, v[136:137]
	v_mov_b32_e32 v131, v0
	s_add_i32 m0, s15, 0x18000
	v_lshl_add_u64 v[2:3], v[2:3], 0, s[84:85]
	v_lshl_add_u64 v[6:7], s[2:3], 0, v[130:131]
	v_mov_b32_e32 v135, v0
	s_and_b32 s13, s8, 3
	s_lshl_b32 s12, s6, 6
	s_waitcnt vmcnt(4)
	s_barrier
	global_load_lds_dwordx4 v[2:3], off
	v_lshl_add_u64 v[2:3], v[4:5], 0, s[84:85]
	s_add_i32 m0, s15, 0x1a000
	s_add_i32 s19, s15, 0x8000
	s_add_i32 s20, s15, 0xa000
	v_lshl_add_u64 v[8:9], s[2:3], 0, v[134:135]
	global_load_lds_dwordx4 v[2:3], off
	v_lshl_add_u64 v[2:3], v[6:7], 0, s[84:85]
	s_mov_b32 m0, s19
	s_add_u32 s8, s0, 0x10080
	global_load_lds_dwordx4 v[2:3], off
	v_lshl_add_u64 v[2:3], v[8:9], 0, s[84:85]
	s_mov_b32 m0, s20
	s_addc_u32 s9, s1, 0
	global_load_lds_dwordx4 v[2:3], off
	s_add_i32 m0, s15, 0x1c000
	v_lshl_add_u64 v[2:3], s[8:9], 0, v[132:133]
	global_load_lds_dwordx4 v[2:3], off
	v_lshl_add_u64 v[2:3], s[8:9], 0, v[136:137]
	s_add_i32 m0, s15, 0x1e000
	v_bfe_u32 v1, v170, 4, 2
	global_load_lds_dwordx4 v[2:3], off
	v_and_b32_e32 v158, 15, v170
	v_lshlrev_b32_e32 v11, 2, v170
	s_waitcnt vmcnt(6)
	v_lshlrev_b32_e32 v146, 4, v1
	v_lshlrev_b32_e32 v10, 6, v158
	v_and_b32_e32 v11, 32, v11
	v_mov_b32_e32 v129, 0
	v_bitop3_b32 v147, v146, v11, v10 bitop3:0x36
	s_cmp_lt_i32 s4, 64
	v_mov_b32_e32 v128, v129
	s_waitcnt vmcnt(0)
	v_mov_b32_e32 v127, v129
	v_mov_b32_e32 v126, v129
	v_mov_b32_e32 v125, v129
	v_mov_b32_e32 v124, v129
	v_mov_b32_e32 v123, v129
	v_mov_b32_e32 v122, v129
	v_mov_b32_e32 v113, v129
	v_mov_b32_e32 v112, v129
	v_mov_b32_e32 v111, v129
	v_mov_b32_e32 v110, v129
	v_mov_b32_e32 v109, v129
	v_mov_b32_e32 v108, v129
	v_mov_b32_e32 v107, v129
	v_mov_b32_e32 v106, v129
	v_mov_b32_e32 v97, v129
	v_mov_b32_e32 v96, v129
	v_mov_b32_e32 v95, v129
	v_mov_b32_e32 v94, v129
	v_mov_b32_e32 v93, v129
	v_mov_b32_e32 v92, v129
	v_mov_b32_e32 v91, v129
	v_mov_b32_e32 v90, v129
	v_mov_b32_e32 v81, v129
	v_mov_b32_e32 v80, v129
	v_mov_b32_e32 v79, v129
	v_mov_b32_e32 v78, v129
	v_mov_b32_e32 v77, v129
	v_mov_b32_e32 v76, v129
	v_mov_b32_e32 v75, v129
	v_mov_b32_e32 v74, v129
	v_mov_b32_e32 v121, v129
	v_mov_b32_e32 v120, v129
	v_mov_b32_e32 v119, v129
	v_mov_b32_e32 v118, v129
	v_mov_b32_e32 v117, v129
	v_mov_b32_e32 v116, v129
	v_mov_b32_e32 v115, v129
	v_mov_b32_e32 v114, v129
	v_mov_b32_e32 v105, v129
	v_mov_b32_e32 v104, v129
	v_mov_b32_e32 v103, v129
	v_mov_b32_e32 v102, v129
	v_mov_b32_e32 v101, v129
	v_mov_b32_e32 v100, v129
	v_mov_b32_e32 v99, v129
	v_mov_b32_e32 v98, v129
	v_mov_b32_e32 v89, v129
	v_mov_b32_e32 v88, v129
	v_mov_b32_e32 v87, v129
	v_mov_b32_e32 v86, v129
	v_mov_b32_e32 v85, v129
	v_mov_b32_e32 v84, v129
	v_mov_b32_e32 v83, v129
	v_mov_b32_e32 v82, v129
	v_mov_b32_e32 v73, v129
	v_mov_b32_e32 v72, v129
	v_mov_b32_e32 v71, v129
	v_mov_b32_e32 v70, v129
	v_mov_b32_e32 v69, v129
	v_mov_b32_e32 v68, v129
	v_mov_b32_e32 v67, v129
	v_mov_b32_e32 v66, v129
	v_mov_b32_e32 v65, v129
	v_mov_b32_e32 v64, v129
	v_mov_b32_e32 v63, v129
	v_mov_b32_e32 v62, v129
	v_mov_b32_e32 v61, v129
	v_mov_b32_e32 v60, v129
	v_mov_b32_e32 v59, v129
	v_mov_b32_e32 v58, v129
	v_mov_b32_e32 v49, v129
	v_mov_b32_e32 v48, v129
	v_mov_b32_e32 v47, v129
	v_mov_b32_e32 v46, v129
	v_mov_b32_e32 v45, v129
	v_mov_b32_e32 v44, v129
	v_mov_b32_e32 v43, v129
	v_mov_b32_e32 v42, v129
	v_mov_b32_e32 v33, v129
	v_mov_b32_e32 v32, v129
	v_mov_b32_e32 v31, v129
	v_mov_b32_e32 v30, v129
	v_mov_b32_e32 v29, v129
	v_mov_b32_e32 v28, v129
	v_mov_b32_e32 v27, v129
	v_mov_b32_e32 v26, v129
	v_mov_b32_e32 v17, v129
	v_mov_b32_e32 v16, v129
	v_mov_b32_e32 v15, v129
	v_mov_b32_e32 v14, v129
	v_mov_b32_e32 v13, v129
	v_mov_b32_e32 v12, v129
	v_mov_b32_e32 v11, v129
	v_mov_b32_e32 v10, v129
	v_mov_b32_e32 v57, v129
	v_mov_b32_e32 v56, v129
	v_mov_b32_e32 v55, v129
	v_mov_b32_e32 v54, v129
	v_mov_b32_e32 v53, v129
	v_mov_b32_e32 v52, v129
	v_mov_b32_e32 v51, v129
	v_mov_b32_e32 v50, v129
	v_mov_b32_e32 v41, v129
	v_mov_b32_e32 v40, v129
	v_mov_b32_e32 v39, v129
	v_mov_b32_e32 v38, v129
	v_mov_b32_e32 v37, v129
	v_mov_b32_e32 v36, v129
	v_mov_b32_e32 v35, v129
	v_mov_b32_e32 v34, v129
	v_mov_b32_e32 v25, v129
	v_mov_b32_e32 v24, v129
	v_mov_b32_e32 v23, v129
	v_mov_b32_e32 v22, v129
	v_mov_b32_e32 v21, v129
	v_mov_b32_e32 v20, v129
	v_mov_b32_e32 v19, v129
	v_mov_b32_e32 v18, v129
	v_mov_b32_e32 v9, v129
	v_mov_b32_e32 v8, v129
	v_mov_b32_e32 v7, v129
	v_mov_b32_e32 v6, v129
	v_mov_b32_e32 v5, v129
	v_mov_b32_e32 v4, v129
	v_mov_b32_e32 v3, v129
	v_mov_b32_e32 v2, v129
	s_barrier
	s_cbranch_scc1 .LBB0_428
	s_ashr_i32 s8, s4, 31
	s_lshr_b32 s8, s8, 26
	s_add_i32 s4, s4, s8
	v_or_b32_e32 v2, s12, v158
	s_ashr_i32 s21, s4, 6
	v_lshlrev_b32_e32 v3, 6, v2
	s_movk_i32 s4, 0x3c0
	v_lshlrev_b32_e32 v2, 2, v2
	v_and_or_b32 v3, v3, s4, v146
	s_lshl_b32 s4, s6, 13
	v_and_b32_e32 v2, 32, v2
	v_bitop3_b32 v4, v3, s4, v2 bitop3:0xde
	v_lshlrev_b32_e32 v2, 12, v138
	s_lshl_b32 s4, s5, 17
	v_and_b32_e32 v2, 0xffffe000, v2
	s_and_b32 s4, s4, 0x1f00000
	s_lshl_b32 s5, s7, 17
	s_add_i32 s22, s21, -2
	v_lshl_add_u32 v2, v139, 9, v2
	v_and_b32_e32 v3, 1, v138
	s_add_i32 s4, s4, s5
	v_lshl_or_b32 v2, v3, 6, v2
	s_add_u32 s4, s66, s4
	v_lshl_add_u32 v2, v140, 1, v2
	v_mov_b32_e32 v3, v0
	s_addc_u32 s5, s67, 0
	v_lshl_add_u64 v[138:139], s[4:5], 0, v[2:3]
	v_lshlrev_b32_e32 v2, 12, v141
	v_and_b32_e32 v2, 0xffffe000, v2
	v_lshl_add_u32 v2, v143, 9, v2
	v_and_b32_e32 v3, 1, v141
	v_lshl_or_b32 v2, v3, 6, v2
	v_lshl_add_u32 v2, v144, 1, v2
	v_mov_b32_e32 v3, v0
	v_lshl_add_u64 v[140:141], s[4:5], 0, v[2:3]
	v_mov_b32_e32 v2, 0
	v_lshl_or_b32 v142, s13, 12, v147
	s_mov_b32 s6, 0
	s_mov_b64 s[4:5], 0x1d410080
	v_add_u32_e32 v143, 0, v4
	v_mov_b32_e32 v3, v2
	v_mov_b32_e32 v4, v2
	v_mov_b32_e32 v5, v2
	v_mov_b32_e32 v6, v2
	v_mov_b32_e32 v7, v2
	v_mov_b32_e32 v8, v2
	v_mov_b32_e32 v9, v2
	v_mov_b32_e32 v18, v2
	v_mov_b32_e32 v19, v2
	v_mov_b32_e32 v20, v2
	v_mov_b32_e32 v21, v2
	v_mov_b32_e32 v22, v2
	v_mov_b32_e32 v23, v2
	v_mov_b32_e32 v24, v2
	v_mov_b32_e32 v25, v2
	v_mov_b32_e32 v34, v2
	v_mov_b32_e32 v35, v2
	v_mov_b32_e32 v36, v2
	v_mov_b32_e32 v37, v2
	v_mov_b32_e32 v38, v2
	v_mov_b32_e32 v39, v2
	v_mov_b32_e32 v40, v2
	v_mov_b32_e32 v41, v2
	v_mov_b32_e32 v50, v2
	v_mov_b32_e32 v51, v2
	v_mov_b32_e32 v52, v2
	v_mov_b32_e32 v53, v2
	v_mov_b32_e32 v54, v2
	v_mov_b32_e32 v55, v2
	v_mov_b32_e32 v56, v2
	v_mov_b32_e32 v57, v2
	v_mov_b32_e32 v10, v2
	v_mov_b32_e32 v11, v2
	v_mov_b32_e32 v12, v2
	v_mov_b32_e32 v13, v2
	v_mov_b32_e32 v14, v2
	v_mov_b32_e32 v15, v2
	v_mov_b32_e32 v16, v2
	v_mov_b32_e32 v17, v2
	v_mov_b32_e32 v26, v2
	v_mov_b32_e32 v27, v2
	v_mov_b32_e32 v28, v2
	v_mov_b32_e32 v29, v2
	v_mov_b32_e32 v30, v2
	v_mov_b32_e32 v31, v2
	v_mov_b32_e32 v32, v2
	v_mov_b32_e32 v33, v2
	v_mov_b32_e32 v42, v2
	v_mov_b32_e32 v43, v2
	v_mov_b32_e32 v44, v2
	v_mov_b32_e32 v45, v2
	v_mov_b32_e32 v46, v2
	v_mov_b32_e32 v47, v2
	v_mov_b32_e32 v48, v2
	v_mov_b32_e32 v49, v2
	v_mov_b32_e32 v58, v2
	v_mov_b32_e32 v59, v2
	v_mov_b32_e32 v60, v2
	v_mov_b32_e32 v61, v2
	v_mov_b32_e32 v62, v2
	v_mov_b32_e32 v63, v2
	v_mov_b32_e32 v64, v2
	v_mov_b32_e32 v65, v2
	v_mov_b32_e32 v66, v2
	v_mov_b32_e32 v67, v2
	v_mov_b32_e32 v68, v2
	v_mov_b32_e32 v69, v2
	v_mov_b32_e32 v70, v2
	v_mov_b32_e32 v71, v2
	v_mov_b32_e32 v72, v2
	v_mov_b32_e32 v73, v2
	v_mov_b32_e32 v82, v2
	v_mov_b32_e32 v83, v2
	v_mov_b32_e32 v84, v2
	v_mov_b32_e32 v85, v2
	v_mov_b32_e32 v86, v2
	v_mov_b32_e32 v87, v2
	v_mov_b32_e32 v88, v2
	v_mov_b32_e32 v89, v2
	v_mov_b32_e32 v98, v2
	v_mov_b32_e32 v99, v2
	v_mov_b32_e32 v100, v2
	v_mov_b32_e32 v101, v2
	v_mov_b32_e32 v102, v2
	v_mov_b32_e32 v103, v2
	v_mov_b32_e32 v104, v2
	v_mov_b32_e32 v105, v2
	v_mov_b32_e32 v114, v2
	v_mov_b32_e32 v115, v2
	v_mov_b32_e32 v116, v2
	v_mov_b32_e32 v117, v2
	v_mov_b32_e32 v118, v2
	v_mov_b32_e32 v119, v2
	v_mov_b32_e32 v120, v2
	v_mov_b32_e32 v121, v2
	v_mov_b32_e32 v74, v2
	v_mov_b32_e32 v75, v2
	v_mov_b32_e32 v76, v2
	v_mov_b32_e32 v77, v2
	v_mov_b32_e32 v78, v2
	v_mov_b32_e32 v79, v2
	v_mov_b32_e32 v80, v2
	v_mov_b32_e32 v81, v2
	v_mov_b32_e32 v90, v2
	v_mov_b32_e32 v91, v2
	v_mov_b32_e32 v92, v2
	v_mov_b32_e32 v93, v2
	v_mov_b32_e32 v94, v2
	v_mov_b32_e32 v95, v2
	v_mov_b32_e32 v96, v2
	v_mov_b32_e32 v97, v2
	v_mov_b32_e32 v106, v2
	v_mov_b32_e32 v107, v2
	v_mov_b32_e32 v108, v2
	v_mov_b32_e32 v109, v2
	v_mov_b32_e32 v110, v2
	v_mov_b32_e32 v111, v2
	v_mov_b32_e32 v112, v2
	v_mov_b32_e32 v113, v2
	v_mov_b32_e32 v122, v2
	v_mov_b32_e32 v123, v2
	v_mov_b32_e32 v124, v2
	v_mov_b32_e32 v125, v2
	v_mov_b32_e32 v126, v2
	v_mov_b32_e32 v127, v2
	v_mov_b32_e32 v128, v2
	v_mov_b32_e32 v129, v2
	.p2alignl 6, 3212836864

.LBB0_437:
	v_mov_b32_e32 v133, v0
	v_lshl_add_u64 v[2:3], s[0:1], 0, v[132:133]
	v_mov_b32_e32 v137, v0
	v_lshl_add_u64 v[4:5], s[0:1], 0, v[136:137]
	v_mov_b32_e32 v131, v0
	s_add_i32 m0, s15, 0x18000
	v_lshl_add_u64 v[2:3], v[2:3], 0, s[84:85]
	v_lshl_add_u64 v[6:7], s[2:3], 0, v[130:131]
	v_mov_b32_e32 v135, v0
	s_and_b32 s13, s8, 3
	s_lshl_b32 s12, s6, 6
	s_waitcnt vmcnt(4)
	s_barrier
	global_load_lds_dwordx4 v[2:3], off
	v_lshl_add_u64 v[2:3], v[4:5], 0, s[84:85]
	s_add_i32 m0, s15, 0x1a000
	s_add_i32 s19, s15, 0x8000
	s_add_i32 s20, s15, 0xa000
	v_lshl_add_u64 v[8:9], s[2:3], 0, v[134:135]
	global_load_lds_dwordx4 v[2:3], off
	v_lshl_add_u64 v[2:3], v[6:7], 0, s[84:85]
	s_mov_b32 m0, s19
	s_add_u32 s8, s0, 0x10080
	global_load_lds_dwordx4 v[2:3], off
	v_lshl_add_u64 v[2:3], v[8:9], 0, s[84:85]
	s_mov_b32 m0, s20
	s_addc_u32 s9, s1, 0
	global_load_lds_dwordx4 v[2:3], off
	s_add_i32 m0, s15, 0x1c000
	v_lshl_add_u64 v[2:3], s[8:9], 0, v[132:133]
	global_load_lds_dwordx4 v[2:3], off
	v_lshl_add_u64 v[2:3], s[8:9], 0, v[136:137]
	s_add_i32 m0, s15, 0x1e000
	v_bfe_u32 v1, v170, 4, 2
	global_load_lds_dwordx4 v[2:3], off
	v_and_b32_e32 v158, 15, v170
	v_lshlrev_b32_e32 v11, 2, v170
	s_waitcnt vmcnt(6)
	v_lshlrev_b32_e32 v146, 4, v1
	v_lshlrev_b32_e32 v10, 6, v158
	v_and_b32_e32 v11, 32, v11
	v_mov_b32_e32 v129, 0
	v_bitop3_b32 v147, v146, v11, v10 bitop3:0x36
	s_cmp_lt_i32 s4, 64
	v_mov_b32_e32 v128, v129
	s_waitcnt vmcnt(0)
	v_mov_b32_e32 v127, v129
	v_mov_b32_e32 v126, v129
	v_mov_b32_e32 v125, v129
	v_mov_b32_e32 v124, v129
	v_mov_b32_e32 v123, v129
	v_mov_b32_e32 v122, v129
	v_mov_b32_e32 v113, v129
	v_mov_b32_e32 v112, v129
	v_mov_b32_e32 v111, v129
	v_mov_b32_e32 v110, v129
	v_mov_b32_e32 v109, v129
	v_mov_b32_e32 v108, v129
	v_mov_b32_e32 v107, v129
	v_mov_b32_e32 v106, v129
	v_mov_b32_e32 v97, v129
	v_mov_b32_e32 v96, v129
	v_mov_b32_e32 v95, v129
	v_mov_b32_e32 v94, v129
	v_mov_b32_e32 v93, v129
	v_mov_b32_e32 v92, v129
	v_mov_b32_e32 v91, v129
	v_mov_b32_e32 v90, v129
	v_mov_b32_e32 v81, v129
	v_mov_b32_e32 v80, v129
	v_mov_b32_e32 v79, v129
	v_mov_b32_e32 v78, v129
	v_mov_b32_e32 v77, v129
	v_mov_b32_e32 v76, v129
	v_mov_b32_e32 v75, v129
	v_mov_b32_e32 v74, v129
	v_mov_b32_e32 v121, v129
	v_mov_b32_e32 v120, v129
	v_mov_b32_e32 v119, v129
	v_mov_b32_e32 v118, v129
	v_mov_b32_e32 v117, v129
	v_mov_b32_e32 v116, v129
	v_mov_b32_e32 v115, v129
	v_mov_b32_e32 v114, v129
	v_mov_b32_e32 v105, v129
	v_mov_b32_e32 v104, v129
	v_mov_b32_e32 v103, v129
	v_mov_b32_e32 v102, v129
	v_mov_b32_e32 v101, v129
	v_mov_b32_e32 v100, v129
	v_mov_b32_e32 v99, v129
	v_mov_b32_e32 v98, v129
	v_mov_b32_e32 v89, v129
	v_mov_b32_e32 v88, v129
	v_mov_b32_e32 v87, v129
	v_mov_b32_e32 v86, v129
	v_mov_b32_e32 v85, v129
	v_mov_b32_e32 v84, v129
	v_mov_b32_e32 v83, v129
	v_mov_b32_e32 v82, v129
	v_mov_b32_e32 v73, v129
	v_mov_b32_e32 v72, v129
	v_mov_b32_e32 v71, v129
	v_mov_b32_e32 v70, v129
	v_mov_b32_e32 v69, v129
	v_mov_b32_e32 v68, v129
	v_mov_b32_e32 v67, v129
	v_mov_b32_e32 v66, v129
	v_mov_b32_e32 v65, v129
	v_mov_b32_e32 v64, v129
	v_mov_b32_e32 v63, v129
	v_mov_b32_e32 v62, v129
	v_mov_b32_e32 v61, v129
	v_mov_b32_e32 v60, v129
	v_mov_b32_e32 v59, v129
	v_mov_b32_e32 v58, v129
	v_mov_b32_e32 v49, v129
	v_mov_b32_e32 v48, v129
	v_mov_b32_e32 v47, v129
	v_mov_b32_e32 v46, v129
	v_mov_b32_e32 v45, v129
	v_mov_b32_e32 v44, v129
	v_mov_b32_e32 v43, v129
	v_mov_b32_e32 v42, v129
	v_mov_b32_e32 v33, v129
	v_mov_b32_e32 v32, v129
	v_mov_b32_e32 v31, v129
	v_mov_b32_e32 v30, v129
	v_mov_b32_e32 v29, v129
	v_mov_b32_e32 v28, v129
	v_mov_b32_e32 v27, v129
	v_mov_b32_e32 v26, v129
	v_mov_b32_e32 v17, v129
	v_mov_b32_e32 v16, v129
	v_mov_b32_e32 v15, v129
	v_mov_b32_e32 v14, v129
	v_mov_b32_e32 v13, v129
	v_mov_b32_e32 v12, v129
	v_mov_b32_e32 v11, v129
	v_mov_b32_e32 v10, v129
	v_mov_b32_e32 v57, v129
	v_mov_b32_e32 v56, v129
	v_mov_b32_e32 v55, v129
	v_mov_b32_e32 v54, v129
	v_mov_b32_e32 v53, v129
	v_mov_b32_e32 v52, v129
	v_mov_b32_e32 v51, v129
	v_mov_b32_e32 v50, v129
	v_mov_b32_e32 v41, v129
	v_mov_b32_e32 v40, v129
	v_mov_b32_e32 v39, v129
	v_mov_b32_e32 v38, v129
	v_mov_b32_e32 v37, v129
	v_mov_b32_e32 v36, v129
	v_mov_b32_e32 v35, v129
	v_mov_b32_e32 v34, v129
	v_mov_b32_e32 v25, v129
	v_mov_b32_e32 v24, v129
	v_mov_b32_e32 v23, v129
	v_mov_b32_e32 v22, v129
	v_mov_b32_e32 v21, v129
	v_mov_b32_e32 v20, v129
	v_mov_b32_e32 v19, v129
	v_mov_b32_e32 v18, v129
	v_mov_b32_e32 v9, v129
	v_mov_b32_e32 v8, v129
	v_mov_b32_e32 v7, v129
	v_mov_b32_e32 v6, v129
	v_mov_b32_e32 v5, v129
	v_mov_b32_e32 v4, v129
	v_mov_b32_e32 v3, v129
	v_mov_b32_e32 v2, v129
	s_barrier
	s_cbranch_scc1 .LBB0_440
	s_ashr_i32 s8, s4, 31
	s_lshr_b32 s8, s8, 26
	s_add_i32 s4, s4, s8
	v_or_b32_e32 v2, s12, v158
	s_ashr_i32 s21, s4, 6
	v_lshlrev_b32_e32 v3, 6, v2
	s_movk_i32 s4, 0x3c0
	v_lshlrev_b32_e32 v2, 2, v2
	v_and_or_b32 v3, v3, s4, v146
	s_lshl_b32 s4, s6, 13
	v_and_b32_e32 v2, 32, v2
	v_bitop3_b32 v4, v3, s4, v2 bitop3:0xde
	v_lshlrev_b32_e32 v2, 12, v138
	s_lshl_b32 s4, s5, 17
	v_and_b32_e32 v2, 0xffffe000, v2
	s_and_b32 s4, s4, 0x1f00000
	s_lshl_b32 s5, s7, 17
	s_add_i32 s22, s21, -2
	v_lshl_add_u32 v2, v139, 9, v2
	v_and_b32_e32 v3, 1, v138
	s_add_i32 s4, s4, s5
	v_lshl_or_b32 v2, v3, 6, v2
	s_add_u32 s4, s66, s4
	v_lshl_add_u32 v2, v140, 1, v2
	v_mov_b32_e32 v3, v0
	s_addc_u32 s5, s67, 0
	v_lshl_add_u64 v[138:139], s[4:5], 0, v[2:3]
	v_lshlrev_b32_e32 v2, 12, v141
	v_and_b32_e32 v2, 0xffffe000, v2
	v_lshl_add_u32 v2, v143, 9, v2
	v_and_b32_e32 v3, 1, v141
	v_lshl_or_b32 v2, v3, 6, v2
	v_lshl_add_u32 v2, v144, 1, v2
	v_mov_b32_e32 v3, v0
	v_lshl_add_u64 v[140:141], s[4:5], 0, v[2:3]
	v_mov_b32_e32 v2, 0
	v_lshl_or_b32 v142, s13, 12, v147
	s_mov_b32 s6, 0
	s_mov_b64 s[4:5], 0x1d210080
	v_add_u32_e32 v143, 0, v4
	v_mov_b32_e32 v3, v2
	v_mov_b32_e32 v4, v2
	v_mov_b32_e32 v5, v2
	v_mov_b32_e32 v6, v2
	v_mov_b32_e32 v7, v2
	v_mov_b32_e32 v8, v2
	v_mov_b32_e32 v9, v2
	v_mov_b32_e32 v18, v2
	v_mov_b32_e32 v19, v2
	v_mov_b32_e32 v20, v2
	v_mov_b32_e32 v21, v2
	v_mov_b32_e32 v22, v2
	v_mov_b32_e32 v23, v2
	v_mov_b32_e32 v24, v2
	v_mov_b32_e32 v25, v2
	v_mov_b32_e32 v34, v2
	v_mov_b32_e32 v35, v2
	v_mov_b32_e32 v36, v2
	v_mov_b32_e32 v37, v2
	v_mov_b32_e32 v38, v2
	v_mov_b32_e32 v39, v2
	v_mov_b32_e32 v40, v2
	v_mov_b32_e32 v41, v2
	v_mov_b32_e32 v50, v2
	v_mov_b32_e32 v51, v2
	v_mov_b32_e32 v52, v2
	v_mov_b32_e32 v53, v2
	v_mov_b32_e32 v54, v2
	v_mov_b32_e32 v55, v2
	v_mov_b32_e32 v56, v2
	v_mov_b32_e32 v57, v2
	v_mov_b32_e32 v10, v2
	v_mov_b32_e32 v11, v2
	v_mov_b32_e32 v12, v2
	v_mov_b32_e32 v13, v2
	v_mov_b32_e32 v14, v2
	v_mov_b32_e32 v15, v2
	v_mov_b32_e32 v16, v2
	v_mov_b32_e32 v17, v2
	v_mov_b32_e32 v26, v2
	v_mov_b32_e32 v27, v2
	v_mov_b32_e32 v28, v2
	v_mov_b32_e32 v29, v2
	v_mov_b32_e32 v30, v2
	v_mov_b32_e32 v31, v2
	v_mov_b32_e32 v32, v2
	v_mov_b32_e32 v33, v2
	v_mov_b32_e32 v42, v2
	v_mov_b32_e32 v43, v2
	v_mov_b32_e32 v44, v2
	v_mov_b32_e32 v45, v2
	v_mov_b32_e32 v46, v2
	v_mov_b32_e32 v47, v2
	v_mov_b32_e32 v48, v2
	v_mov_b32_e32 v49, v2
	v_mov_b32_e32 v58, v2
	v_mov_b32_e32 v59, v2
	v_mov_b32_e32 v60, v2
	v_mov_b32_e32 v61, v2
	v_mov_b32_e32 v62, v2
	v_mov_b32_e32 v63, v2
	v_mov_b32_e32 v64, v2
	v_mov_b32_e32 v65, v2
	v_mov_b32_e32 v66, v2
	v_mov_b32_e32 v67, v2
	v_mov_b32_e32 v68, v2
	v_mov_b32_e32 v69, v2
	v_mov_b32_e32 v70, v2
	v_mov_b32_e32 v71, v2
	v_mov_b32_e32 v72, v2
	v_mov_b32_e32 v73, v2
	v_mov_b32_e32 v82, v2
	v_mov_b32_e32 v83, v2
	v_mov_b32_e32 v84, v2
	v_mov_b32_e32 v85, v2
	v_mov_b32_e32 v86, v2
	v_mov_b32_e32 v87, v2
	v_mov_b32_e32 v88, v2
	v_mov_b32_e32 v89, v2
	v_mov_b32_e32 v98, v2
	v_mov_b32_e32 v99, v2
	v_mov_b32_e32 v100, v2
	v_mov_b32_e32 v101, v2
	v_mov_b32_e32 v102, v2
	v_mov_b32_e32 v103, v2
	v_mov_b32_e32 v104, v2
	v_mov_b32_e32 v105, v2
	v_mov_b32_e32 v114, v2
	v_mov_b32_e32 v115, v2
	v_mov_b32_e32 v116, v2
	v_mov_b32_e32 v117, v2
	v_mov_b32_e32 v118, v2
	v_mov_b32_e32 v119, v2
	v_mov_b32_e32 v120, v2
	v_mov_b32_e32 v121, v2
	v_mov_b32_e32 v74, v2
	v_mov_b32_e32 v75, v2
	v_mov_b32_e32 v76, v2
	v_mov_b32_e32 v77, v2
	v_mov_b32_e32 v78, v2
	v_mov_b32_e32 v79, v2
	v_mov_b32_e32 v80, v2
	v_mov_b32_e32 v81, v2
	v_mov_b32_e32 v90, v2
	v_mov_b32_e32 v91, v2
	v_mov_b32_e32 v92, v2
	v_mov_b32_e32 v93, v2
	v_mov_b32_e32 v94, v2
	v_mov_b32_e32 v95, v2
	v_mov_b32_e32 v96, v2
	v_mov_b32_e32 v97, v2
	v_mov_b32_e32 v106, v2
	v_mov_b32_e32 v107, v2
	v_mov_b32_e32 v108, v2
	v_mov_b32_e32 v109, v2
	v_mov_b32_e32 v110, v2
	v_mov_b32_e32 v111, v2
	v_mov_b32_e32 v112, v2
	v_mov_b32_e32 v113, v2
	v_mov_b32_e32 v122, v2
	v_mov_b32_e32 v123, v2
	v_mov_b32_e32 v124, v2
	v_mov_b32_e32 v125, v2
	v_mov_b32_e32 v126, v2
	v_mov_b32_e32 v127, v2
	v_mov_b32_e32 v128, v2
	v_mov_b32_e32 v129, v2
	.p2alignl 6, 3212836864

.LBB0_452:
	s_ashr_i32 s11, s10, 31
	s_lshl_b64 s[12:13], s[10:11], 19
	s_add_u32 s12, s64, s12
	s_addc_u32 s13, s65, s13
	s_ashr_i32 s9, s8, 31
	s_lshl_b64 s[14:15], s[8:9], 19
	s_add_u32 s14, s25, s14
	s_waitcnt vmcnt(0)
	v_mov_b32_e32 v121, 0
	s_addc_u32 s15, s26, s15
	s_andn2_b64 vcc, exec, s[6:7]
	v_mov_b32_e32 v120, v121
	v_mov_b32_e32 v119, v121
	v_mov_b32_e32 v118, v121
	v_mov_b32_e32 v125, v121
	v_mov_b32_e32 v124, v121
	v_mov_b32_e32 v123, v121
	v_mov_b32_e32 v122, v121
	v_mov_b32_e32 v105, v121
	v_mov_b32_e32 v104, v121
	v_mov_b32_e32 v103, v121
	v_mov_b32_e32 v102, v121
	v_mov_b32_e32 v109, v121
	v_mov_b32_e32 v108, v121
	v_mov_b32_e32 v107, v121
	v_mov_b32_e32 v106, v121
	v_mov_b32_e32 v89, v121
	v_mov_b32_e32 v88, v121
	v_mov_b32_e32 v87, v121
	v_mov_b32_e32 v86, v121
	v_mov_b32_e32 v93, v121
	v_mov_b32_e32 v92, v121
	v_mov_b32_e32 v91, v121
	v_mov_b32_e32 v90, v121
	v_mov_b32_e32 v73, v121
	v_mov_b32_e32 v72, v121
	v_mov_b32_e32 v71, v121
	v_mov_b32_e32 v70, v121
	v_mov_b32_e32 v77, v121
	v_mov_b32_e32 v76, v121
	v_mov_b32_e32 v75, v121
	v_mov_b32_e32 v74, v121
	v_mov_b32_e32 v117, v121
	v_mov_b32_e32 v116, v121
	v_mov_b32_e32 v115, v121
	v_mov_b32_e32 v114, v121
	v_mov_b32_e32 v129, v121
	v_mov_b32_e32 v128, v121
	v_mov_b32_e32 v127, v121
	v_mov_b32_e32 v126, v121
	v_mov_b32_e32 v101, v121
	v_mov_b32_e32 v100, v121
	v_mov_b32_e32 v99, v121
	v_mov_b32_e32 v98, v121
	v_mov_b32_e32 v113, v121
	v_mov_b32_e32 v112, v121
	v_mov_b32_e32 v111, v121
	v_mov_b32_e32 v110, v121
	v_mov_b32_e32 v85, v121
	v_mov_b32_e32 v84, v121
	v_mov_b32_e32 v83, v121
	v_mov_b32_e32 v82, v121
	v_mov_b32_e32 v97, v121
	v_mov_b32_e32 v96, v121
	v_mov_b32_e32 v95, v121
	v_mov_b32_e32 v94, v121
	v_mov_b32_e32 v69, v121
	v_mov_b32_e32 v68, v121
	v_mov_b32_e32 v67, v121
	v_mov_b32_e32 v66, v121
	v_mov_b32_e32 v81, v121
	v_mov_b32_e32 v80, v121
	v_mov_b32_e32 v79, v121
	v_mov_b32_e32 v78, v121
	v_mov_b32_e32 v57, v121
	v_mov_b32_e32 v56, v121
	v_mov_b32_e32 v55, v121
	v_mov_b32_e32 v54, v121
	v_mov_b32_e32 v61, v121
	v_mov_b32_e32 v60, v121
	v_mov_b32_e32 v59, v121
	v_mov_b32_e32 v58, v121
	v_mov_b32_e32 v41, v121
	v_mov_b32_e32 v40, v121
	v_mov_b32_e32 v39, v121
	v_mov_b32_e32 v38, v121
	v_mov_b32_e32 v45, v121
	v_mov_b32_e32 v44, v121
	v_mov_b32_e32 v43, v121
	v_mov_b32_e32 v42, v121
	v_mov_b32_e32 v25, v121
	v_mov_b32_e32 v24, v121
	v_mov_b32_e32 v23, v121
	v_mov_b32_e32 v22, v121
	v_mov_b32_e32 v29, v121
	v_mov_b32_e32 v28, v121
	v_mov_b32_e32 v27, v121
	v_mov_b32_e32 v26, v121
	v_mov_b32_e32 v13, v121
	v_mov_b32_e32 v12, v121
	v_mov_b32_e32 v11, v121
	v_mov_b32_e32 v10, v121
	v_mov_b32_e32 v17, v121
	v_mov_b32_e32 v16, v121
	v_mov_b32_e32 v15, v121
	v_mov_b32_e32 v14, v121
	v_mov_b32_e32 v53, v121
	v_mov_b32_e32 v52, v121
	v_mov_b32_e32 v51, v121
	v_mov_b32_e32 v50, v121
	v_mov_b32_e32 v65, v121
	v_mov_b32_e32 v64, v121
	v_mov_b32_e32 v63, v121
	v_mov_b32_e32 v62, v121
	v_mov_b32_e32 v37, v121
	v_mov_b32_e32 v36, v121
	v_mov_b32_e32 v35, v121
	v_mov_b32_e32 v34, v121
	v_mov_b32_e32 v49, v121
	v_mov_b32_e32 v48, v121
	v_mov_b32_e32 v47, v121
	v_mov_b32_e32 v46, v121
	v_mov_b32_e32 v21, v121
	v_mov_b32_e32 v20, v121
	v_mov_b32_e32 v19, v121
	v_mov_b32_e32 v18, v121
	v_mov_b32_e32 v33, v121
	v_mov_b32_e32 v32, v121
	v_mov_b32_e32 v31, v121
	v_mov_b32_e32 v30, v121
	v_mov_b32_e32 v5, v121
	v_mov_b32_e32 v4, v121
	v_mov_b32_e32 v3, v121
	v_mov_b32_e32 v2, v121
	v_mov_b32_e32 v9, v121
	v_mov_b32_e32 v8, v121
	v_mov_b32_e32 v7, v121
	v_mov_b32_e32 v6, v121
	s_cbranch_vccnz .LBB0_455
	v_mov_b64_e32 v[2:3], 0x280
	v_cmp_lt_i64_e32 vcc, s[22:23], v[2:3]
	s_and_b64 s[22:23], vcc, exec
	s_cselect_b32 s9, s13, s19
	s_cselect_b32 s11, s12, s18
	s_cselect_b32 s48, s15, s21
	s_cselect_b32 s49, s14, s20
	s_add_u32 s18, s18, 0x40080
	s_addc_u32 s19, s19, 0
	s_add_u32 s50, s20, 0x100
	v_mov_b32_e32 v6, 0
	s_addc_u32 s51, s21, 0
	s_mov_b32 s20, 0
	v_mov_b32_e32 v7, v6
	v_mov_b32_e32 v8, v6
	v_mov_b32_e32 v9, v6
	v_mov_b32_e32 v2, v6
	v_mov_b32_e32 v3, v6
	v_mov_b32_e32 v4, v6
	v_mov_b32_e32 v5, v6
	v_mov_b32_e32 v30, v6
	v_mov_b32_e32 v31, v6
	v_mov_b32_e32 v32, v6
	v_mov_b32_e32 v33, v6
	v_mov_b32_e32 v18, v6
	v_mov_b32_e32 v19, v6
	v_mov_b32_e32 v20, v6
	v_mov_b32_e32 v21, v6
	v_mov_b32_e32 v46, v6
	v_mov_b32_e32 v47, v6
	v_mov_b32_e32 v48, v6
	v_mov_b32_e32 v49, v6
	v_mov_b32_e32 v34, v6
	v_mov_b32_e32 v35, v6
	v_mov_b32_e32 v36, v6
	v_mov_b32_e32 v37, v6
	v_mov_b32_e32 v62, v6
	v_mov_b32_e32 v63, v6
	v_mov_b32_e32 v64, v6
	v_mov_b32_e32 v65, v6
	v_mov_b32_e32 v50, v6
	v_mov_b32_e32 v51, v6
	v_mov_b32_e32 v52, v6
	v_mov_b32_e32 v53, v6
	v_mov_b32_e32 v14, v6
	v_mov_b32_e32 v15, v6
	v_mov_b32_e32 v16, v6
	v_mov_b32_e32 v17, v6
	v_mov_b32_e32 v10, v6
	v_mov_b32_e32 v11, v6
	v_mov_b32_e32 v12, v6
	v_mov_b32_e32 v13, v6
	v_mov_b32_e32 v26, v6
	v_mov_b32_e32 v27, v6
	v_mov_b32_e32 v28, v6
	v_mov_b32_e32 v29, v6
	v_mov_b32_e32 v22, v6
	v_mov_b32_e32 v23, v6
	v_mov_b32_e32 v24, v6
	v_mov_b32_e32 v25, v6
	v_mov_b32_e32 v42, v6
	v_mov_b32_e32 v43, v6
	v_mov_b32_e32 v44, v6
	v_mov_b32_e32 v45, v6
	v_mov_b32_e32 v38, v6
	v_mov_b32_e32 v39, v6
	v_mov_b32_e32 v40, v6
	v_mov_b32_e32 v41, v6
	v_mov_b32_e32 v58, v6
	v_mov_b32_e32 v59, v6
	v_mov_b32_e32 v60, v6
	v_mov_b32_e32 v61, v6
	v_mov_b32_e32 v54, v6
	v_mov_b32_e32 v55, v6
	v_mov_b32_e32 v56, v6
	v_mov_b32_e32 v57, v6
	v_mov_b32_e32 v78, v6
	v_mov_b32_e32 v79, v6
	v_mov_b32_e32 v80, v6
	v_mov_b32_e32 v81, v6
	v_mov_b32_e32 v66, v6
	v_mov_b32_e32 v67, v6
	v_mov_b32_e32 v68, v6
	v_mov_b32_e32 v69, v6
	v_mov_b32_e32 v94, v6
	v_mov_b32_e32 v95, v6
	v_mov_b32_e32 v96, v6
	v_mov_b32_e32 v97, v6
	v_mov_b32_e32 v82, v6
	v_mov_b32_e32 v83, v6
	v_mov_b32_e32 v84, v6
	v_mov_b32_e32 v85, v6
	v_mov_b32_e32 v110, v6
	v_mov_b32_e32 v111, v6
	v_mov_b32_e32 v112, v6
	v_mov_b32_e32 v113, v6
	v_mov_b32_e32 v98, v6
	v_mov_b32_e32 v99, v6
	v_mov_b32_e32 v100, v6
	v_mov_b32_e32 v101, v6
	v_mov_b32_e32 v126, v6
	v_mov_b32_e32 v127, v6
	v_mov_b32_e32 v128, v6
	v_mov_b32_e32 v129, v6
	v_mov_b32_e32 v114, v6
	v_mov_b32_e32 v115, v6
	v_mov_b32_e32 v116, v6
	v_mov_b32_e32 v117, v6
	v_mov_b32_e32 v74, v6
	v_mov_b32_e32 v75, v6
	v_mov_b32_e32 v76, v6
	v_mov_b32_e32 v77, v6
	v_mov_b32_e32 v70, v6
	v_mov_b32_e32 v71, v6
	v_mov_b32_e32 v72, v6
	v_mov_b32_e32 v73, v6
	v_mov_b32_e32 v90, v6
	v_mov_b32_e32 v91, v6
	v_mov_b32_e32 v92, v6
	v_mov_b32_e32 v93, v6
	v_mov_b32_e32 v86, v6
	v_mov_b32_e32 v87, v6
	v_mov_b32_e32 v88, v6
	v_mov_b32_e32 v89, v6
	v_mov_b32_e32 v106, v6
	v_mov_b32_e32 v107, v6
	v_mov_b32_e32 v108, v6
	v_mov_b32_e32 v109, v6
	v_mov_b32_e32 v102, v6
	v_mov_b32_e32 v103, v6
	v_mov_b32_e32 v104, v6
	v_mov_b32_e32 v105, v6
	v_mov_b32_e32 v122, v6
	v_mov_b32_e32 v123, v6
	v_mov_b32_e32 v124, v6
	v_mov_b32_e32 v125, v6
	v_mov_b32_e32 v118, v6
	v_mov_b32_e32 v119, v6
	v_mov_b32_e32 v120, v6
	v_mov_b32_e32 v121, v6
	.p2alignl 6, 3212836864

.LBB0_498:
	v_mov_b32_e32 v145, 0
	s_andn2_b64 vcc, exec, s[6:7]
	v_mov_b32_e32 v144, v145
	v_mov_b32_e32 v143, v145
	v_mov_b32_e32 v142, v145
	v_mov_b32_e32 v141, v145
	v_mov_b32_e32 v140, v145
	v_mov_b32_e32 v139, v145
	v_mov_b32_e32 v138, v145
	v_mov_b32_e32 v129, v145
	v_mov_b32_e32 v128, v145
	v_mov_b32_e32 v127, v145
	v_mov_b32_e32 v126, v145
	v_mov_b32_e32 v121, v145
	v_mov_b32_e32 v120, v145
	v_mov_b32_e32 v119, v145
	v_mov_b32_e32 v118, v145
	v_mov_b32_e32 v97, v145
	v_mov_b32_e32 v96, v145
	v_mov_b32_e32 v95, v145
	v_mov_b32_e32 v94, v145
	v_mov_b32_e32 v93, v145
	v_mov_b32_e32 v92, v145
	v_mov_b32_e32 v91, v145
	v_mov_b32_e32 v90, v145
	v_mov_b32_e32 v81, v145
	v_mov_b32_e32 v80, v145
	v_mov_b32_e32 v79, v145
	v_mov_b32_e32 v78, v145
	v_mov_b32_e32 v77, v145
	v_mov_b32_e32 v76, v145
	v_mov_b32_e32 v75, v145
	v_mov_b32_e32 v74, v145
	v_mov_b32_e32 v137, v145
	v_mov_b32_e32 v136, v145
	v_mov_b32_e32 v135, v145
	v_mov_b32_e32 v134, v145
	v_mov_b32_e32 v133, v145
	v_mov_b32_e32 v132, v145
	v_mov_b32_e32 v131, v145
	v_mov_b32_e32 v130, v145
	v_mov_b32_e32 v113, v145
	v_mov_b32_e32 v112, v145
	v_mov_b32_e32 v111, v145
	v_mov_b32_e32 v110, v145
	v_mov_b32_e32 v105, v145
	v_mov_b32_e32 v104, v145
	v_mov_b32_e32 v103, v145
	v_mov_b32_e32 v102, v145
	v_mov_b32_e32 v89, v145
	v_mov_b32_e32 v88, v145
	v_mov_b32_e32 v87, v145
	v_mov_b32_e32 v86, v145
	v_mov_b32_e32 v85, v145
	v_mov_b32_e32 v84, v145
	v_mov_b32_e32 v83, v145
	v_mov_b32_e32 v82, v145
	v_mov_b32_e32 v73, v145
	v_mov_b32_e32 v72, v145
	v_mov_b32_e32 v71, v145
	v_mov_b32_e32 v70, v145
	v_mov_b32_e32 v69, v145
	v_mov_b32_e32 v68, v145
	v_mov_b32_e32 v67, v145
	v_mov_b32_e32 v66, v145
	v_mov_b32_e32 v65, v145
	v_mov_b32_e32 v64, v145
	v_mov_b32_e32 v63, v145
	v_mov_b32_e32 v62, v145
	v_mov_b32_e32 v61, v145
	v_mov_b32_e32 v60, v145
	v_mov_b32_e32 v59, v145
	v_mov_b32_e32 v58, v145
	v_mov_b32_e32 v49, v145
	v_mov_b32_e32 v48, v145
	v_mov_b32_e32 v47, v145
	v_mov_b32_e32 v46, v145
	v_mov_b32_e32 v45, v145
	v_mov_b32_e32 v44, v145
	v_mov_b32_e32 v43, v145
	v_mov_b32_e32 v42, v145
	v_mov_b32_e32 v33, v145
	v_mov_b32_e32 v32, v145
	v_mov_b32_e32 v31, v145
	v_mov_b32_e32 v30, v145
	v_mov_b32_e32 v29, v145
	v_mov_b32_e32 v28, v145
	v_mov_b32_e32 v27, v145
	v_mov_b32_e32 v26, v145
	v_mov_b32_e32 v17, v145
	v_mov_b32_e32 v16, v145
	v_mov_b32_e32 v15, v145
	v_mov_b32_e32 v14, v145
	v_mov_b32_e32 v13, v145
	v_mov_b32_e32 v12, v145
	v_mov_b32_e32 v11, v145
	v_mov_b32_e32 v10, v145
	v_mov_b32_e32 v57, v145
	v_mov_b32_e32 v56, v145
	v_mov_b32_e32 v55, v145
	v_mov_b32_e32 v54, v145
	v_mov_b32_e32 v53, v145
	v_mov_b32_e32 v52, v145
	v_mov_b32_e32 v51, v145
	v_mov_b32_e32 v50, v145
	v_mov_b32_e32 v41, v145
	v_mov_b32_e32 v40, v145
	v_mov_b32_e32 v39, v145
	v_mov_b32_e32 v38, v145
	v_mov_b32_e32 v37, v145
	v_mov_b32_e32 v36, v145
	v_mov_b32_e32 v35, v145
	v_mov_b32_e32 v34, v145
	v_mov_b32_e32 v25, v145
	v_mov_b32_e32 v24, v145
	v_mov_b32_e32 v23, v145
	v_mov_b32_e32 v22, v145
	v_mov_b32_e32 v21, v145
	v_mov_b32_e32 v20, v145
	v_mov_b32_e32 v19, v145
	v_mov_b32_e32 v18, v145
	v_mov_b32_e32 v9, v145
	v_mov_b32_e32 v8, v145
	v_mov_b32_e32 v7, v145
	v_mov_b32_e32 v6, v145
	v_mov_b32_e32 v5, v145
	v_mov_b32_e32 v4, v145
	s_waitcnt lgkmcnt(0)
	v_mov_b32_e32 v3, v145
	v_mov_b32_e32 v2, v145
	s_cbranch_vccnz .LBB0_501
	s_add_u32 s45, s8, 0x100
	s_addc_u32 s46, s9, 0
	s_add_u32 s8, s10, 0xc000
	v_mov_b32_e32 v2, 0
	s_addc_u32 s9, s11, 0
	s_mov_b32 s10, 0
	v_mov_b32_e32 v3, v2
	v_mov_b32_e32 v4, v2
	v_mov_b32_e32 v5, v2
	v_mov_b32_e32 v6, v2
	v_mov_b32_e32 v7, v2
	v_mov_b32_e32 v8, v2
	v_mov_b32_e32 v9, v2
	v_mov_b32_e32 v18, v2
	v_mov_b32_e32 v19, v2
	v_mov_b32_e32 v20, v2
	v_mov_b32_e32 v21, v2
	v_mov_b32_e32 v22, v2
	v_mov_b32_e32 v23, v2
	v_mov_b32_e32 v24, v2
	v_mov_b32_e32 v25, v2
	v_mov_b32_e32 v34, v2
	v_mov_b32_e32 v35, v2
	v_mov_b32_e32 v36, v2
	v_mov_b32_e32 v37, v2
	v_mov_b32_e32 v38, v2
	v_mov_b32_e32 v39, v2
	v_mov_b32_e32 v40, v2
	v_mov_b32_e32 v41, v2
	v_mov_b32_e32 v50, v2
	v_mov_b32_e32 v51, v2
	v_mov_b32_e32 v52, v2
	v_mov_b32_e32 v53, v2
	v_mov_b32_e32 v54, v2
	v_mov_b32_e32 v55, v2
	v_mov_b32_e32 v56, v2
	v_mov_b32_e32 v57, v2
	v_mov_b32_e32 v10, v2
	v_mov_b32_e32 v11, v2
	v_mov_b32_e32 v12, v2
	v_mov_b32_e32 v13, v2
	v_mov_b32_e32 v14, v2
	v_mov_b32_e32 v15, v2
	v_mov_b32_e32 v16, v2
	v_mov_b32_e32 v17, v2
	v_mov_b32_e32 v26, v2
	v_mov_b32_e32 v27, v2
	v_mov_b32_e32 v28, v2
	v_mov_b32_e32 v29, v2
	v_mov_b32_e32 v30, v2
	v_mov_b32_e32 v31, v2
	v_mov_b32_e32 v32, v2
	v_mov_b32_e32 v33, v2
	v_mov_b32_e32 v42, v2
	v_mov_b32_e32 v43, v2
	v_mov_b32_e32 v44, v2
	v_mov_b32_e32 v45, v2
	v_mov_b32_e32 v46, v2
	v_mov_b32_e32 v47, v2
	v_mov_b32_e32 v48, v2
	v_mov_b32_e32 v49, v2
	v_mov_b32_e32 v58, v2
	v_mov_b32_e32 v59, v2
	v_mov_b32_e32 v60, v2
	v_mov_b32_e32 v61, v2
	v_mov_b32_e32 v62, v2
	v_mov_b32_e32 v63, v2
	v_mov_b32_e32 v64, v2
	v_mov_b32_e32 v65, v2
	v_mov_b32_e32 v66, v2
	v_mov_b32_e32 v67, v2
	v_mov_b32_e32 v68, v2
	v_mov_b32_e32 v69, v2
	v_mov_b32_e32 v70, v2
	v_mov_b32_e32 v71, v2
	v_mov_b32_e32 v72, v2
	v_mov_b32_e32 v73, v2
	v_mov_b32_e32 v82, v2
	v_mov_b32_e32 v83, v2
	v_mov_b32_e32 v84, v2
	v_mov_b32_e32 v85, v2
	v_mov_b32_e32 v86, v2
	v_mov_b32_e32 v87, v2
	v_mov_b32_e32 v88, v2
	v_mov_b32_e32 v89, v2
	v_mov_b32_e32 v102, v2
	v_mov_b32_e32 v103, v2
	v_mov_b32_e32 v104, v2
	v_mov_b32_e32 v105, v2
	v_mov_b32_e32 v110, v2
	v_mov_b32_e32 v111, v2
	v_mov_b32_e32 v112, v2
	v_mov_b32_e32 v113, v2
	v_mov_b32_e32 v130, v2
	v_mov_b32_e32 v131, v2
	v_mov_b32_e32 v132, v2
	v_mov_b32_e32 v133, v2
	v_mov_b32_e32 v134, v2
	v_mov_b32_e32 v135, v2
	v_mov_b32_e32 v136, v2
	v_mov_b32_e32 v137, v2
	v_mov_b32_e32 v74, v2
	v_mov_b32_e32 v75, v2
	v_mov_b32_e32 v76, v2
	v_mov_b32_e32 v77, v2
	v_mov_b32_e32 v78, v2
	v_mov_b32_e32 v79, v2
	v_mov_b32_e32 v80, v2
	v_mov_b32_e32 v81, v2
	v_mov_b32_e32 v90, v2
	v_mov_b32_e32 v91, v2
	v_mov_b32_e32 v92, v2
	v_mov_b32_e32 v93, v2
	v_mov_b32_e32 v94, v2
	v_mov_b32_e32 v95, v2
	v_mov_b32_e32 v96, v2
	v_mov_b32_e32 v97, v2
	v_mov_b32_e32 v118, v2
	v_mov_b32_e32 v119, v2
	v_mov_b32_e32 v120, v2
	v_mov_b32_e32 v121, v2
	v_mov_b32_e32 v126, v2
	v_mov_b32_e32 v127, v2
	v_mov_b32_e32 v128, v2
	v_mov_b32_e32 v129, v2
	v_mov_b32_e32 v138, v2
	v_mov_b32_e32 v139, v2
	v_mov_b32_e32 v140, v2
	v_mov_b32_e32 v141, v2
	v_mov_b32_e32 v142, v2
	v_mov_b32_e32 v143, v2
	v_mov_b32_e32 v144, v2
	v_mov_b32_e32 v145, v2
	.p2alignl 6, 3212836864

.LBB0_532:
	s_ashr_i32 s13, s12, 31
	s_lshl_b64 s[14:15], s[12:13], 19
	s_add_u32 s14, s27, s14
	s_addc_u32 s15, s28, s15
	s_ashr_i32 s11, s10, 31
	s_lshl_b64 s[16:17], s[10:11], 19
	s_add_u32 s16, s29, s16
	v_mov_b32_e32 v145, 0
	s_addc_u32 s17, s30, s17
	s_andn2_b64 vcc, exec, s[6:7]
	v_mov_b32_e32 v144, v145
	v_mov_b32_e32 v143, v145
	v_mov_b32_e32 v142, v145
	v_mov_b32_e32 v137, v145
	v_mov_b32_e32 v136, v145
	v_mov_b32_e32 v135, v145
	v_mov_b32_e32 v134, v145
	v_mov_b32_e32 v129, v145
	v_mov_b32_e32 v128, v145
	s_waitcnt vmcnt(0)
	v_mov_b32_e32 v127, v145
	v_mov_b32_e32 v126, v145
	v_mov_b32_e32 v121, v145
	v_mov_b32_e32 v120, v145
	v_mov_b32_e32 v119, v145
	v_mov_b32_e32 v118, v145
	v_mov_b32_e32 v113, v145
	v_mov_b32_e32 v112, v145
	v_mov_b32_e32 v111, v145
	v_mov_b32_e32 v110, v145
	v_mov_b32_e32 v105, v145
	v_mov_b32_e32 v104, v145
	v_mov_b32_e32 v103, v145
	v_mov_b32_e32 v102, v145
	v_mov_b32_e32 v97, v145
	v_mov_b32_e32 v96, v145
	v_mov_b32_e32 v95, v145
	v_mov_b32_e32 v94, v145
	v_mov_b32_e32 v89, v145
	v_mov_b32_e32 v88, v145
	v_mov_b32_e32 v87, v145
	v_mov_b32_e32 v86, v145
	v_mov_b32_e32 v141, v145
	v_mov_b32_e32 v140, v145
	v_mov_b32_e32 v139, v145
	v_mov_b32_e32 v138, v145
	v_mov_b32_e32 v133, v145
	v_mov_b32_e32 v132, v145
	v_mov_b32_e32 v131, v145
	v_mov_b32_e32 v130, v145
	v_mov_b32_e32 v125, v145
	v_mov_b32_e32 v124, v145
	v_mov_b32_e32 v123, v145
	v_mov_b32_e32 v122, v145
	v_mov_b32_e32 v117, v145
	v_mov_b32_e32 v116, v145
	v_mov_b32_e32 v115, v145
	v_mov_b32_e32 v114, v145
	v_mov_b32_e32 v109, v145
	v_mov_b32_e32 v108, v145
	v_mov_b32_e32 v107, v145
	v_mov_b32_e32 v106, v145
	v_mov_b32_e32 v101, v145
	v_mov_b32_e32 v100, v145
	v_mov_b32_e32 v99, v145
	v_mov_b32_e32 v98, v145
	v_mov_b32_e32 v93, v145
	v_mov_b32_e32 v92, v145
	v_mov_b32_e32 v91, v145
	v_mov_b32_e32 v90, v145
	v_mov_b32_e32 v85, v145
	v_mov_b32_e32 v84, v145
	v_mov_b32_e32 v83, v145
	v_mov_b32_e32 v82, v145
	v_mov_b32_e32 v81, v145
	v_mov_b32_e32 v80, v145
	v_mov_b32_e32 v79, v145
	v_mov_b32_e32 v78, v145
	v_mov_b32_e32 v73, v145
	v_mov_b32_e32 v72, v145
	v_mov_b32_e32 v71, v145
	v_mov_b32_e32 v70, v145
	v_mov_b32_e32 v57, v145
	v_mov_b32_e32 v56, v145
	v_mov_b32_e32 v55, v145
	v_mov_b32_e32 v54, v145
	v_mov_b32_e32 v49, v145
	v_mov_b32_e32 v48, v145
	v_mov_b32_e32 v47, v145
	v_mov_b32_e32 v46, v145
	v_mov_b32_e32 v33, v145
	v_mov_b32_e32 v32, v145
	v_mov_b32_e32 v31, v145
	v_mov_b32_e32 v30, v145
	v_mov_b32_e32 v25, v145
	v_mov_b32_e32 v24, v145
	v_mov_b32_e32 v23, v145
	v_mov_b32_e32 v22, v145
	v_mov_b32_e32 v17, v145
	v_mov_b32_e32 v16, v145
	v_mov_b32_e32 v15, v145
	v_mov_b32_e32 v14, v145
	v_mov_b32_e32 v9, v145
	v_mov_b32_e32 v8, v145
	v_mov_b32_e32 v7, v145
	v_mov_b32_e32 v6, v145
	v_mov_b32_e32 v77, v145
	v_mov_b32_e32 v76, v145
	v_mov_b32_e32 v75, v145
	v_mov_b32_e32 v74, v145
	v_mov_b32_e32 v69, v145
	v_mov_b32_e32 v68, v145
	v_mov_b32_e32 v67, v145
	v_mov_b32_e32 v66, v145
	v_mov_b32_e32 v53, v145
	v_mov_b32_e32 v52, v145
	v_mov_b32_e32 v51, v145
	v_mov_b32_e32 v50, v145
	v_mov_b32_e32 v45, v145
	v_mov_b32_e32 v44, v145
	v_mov_b32_e32 v43, v145
	v_mov_b32_e32 v42, v145
	v_mov_b32_e32 v29, v145
	v_mov_b32_e32 v28, v145
	v_mov_b32_e32 v27, v145
	v_mov_b32_e32 v26, v145
	v_mov_b32_e32 v21, v145
	v_mov_b32_e32 v20, v145
	v_mov_b32_e32 v19, v145
	v_mov_b32_e32 v18, v145
	v_mov_b32_e32 v13, v145
	v_mov_b32_e32 v12, v145
	v_mov_b32_e32 v11, v145
	v_mov_b32_e32 v10, v145
	v_mov_b32_e32 v5, v145
	v_mov_b32_e32 v4, v145
	v_mov_b32_e32 v3, v145
	v_mov_b32_e32 v2, v145
	s_cbranch_vccnz .LBB0_535
	v_mov_b64_e32 v[2:3], 0x180
	v_cmp_lt_i64_e32 vcc, s[24:25], v[2:3]
	s_and_b64 s[24:25], vcc, exec
	s_cselect_b32 s11, s15, s21
	s_cselect_b32 s13, s14, s20
	s_cselect_b32 s19, s17, s23
	s_cselect_b32 s38, s16, s22
	s_add_u32 s20, s20, 0x40080
	s_addc_u32 s21, s21, 0
	s_add_u32 s39, s22, 0x100
	v_mov_b32_e32 v2, 0
	s_addc_u32 s56, s23, 0
	s_mov_b32 s22, 0
	v_mov_b32_e32 v3, v2
	v_mov_b32_e32 v4, v2
	v_mov_b32_e32 v5, v2
	v_mov_b32_e32 v10, v2
	v_mov_b32_e32 v11, v2
	v_mov_b32_e32 v12, v2
	v_mov_b32_e32 v13, v2
	v_mov_b32_e32 v18, v2
	v_mov_b32_e32 v19, v2
	v_mov_b32_e32 v20, v2
	v_mov_b32_e32 v21, v2
	v_mov_b32_e32 v26, v2
	v_mov_b32_e32 v27, v2
	v_mov_b32_e32 v28, v2
	v_mov_b32_e32 v29, v2
	v_mov_b32_e32 v42, v2
	v_mov_b32_e32 v43, v2
	v_mov_b32_e32 v44, v2
	v_mov_b32_e32 v45, v2
	v_mov_b32_e32 v50, v2
	v_mov_b32_e32 v51, v2
	v_mov_b32_e32 v52, v2
	v_mov_b32_e32 v53, v2
	v_mov_b32_e32 v66, v2
	v_mov_b32_e32 v67, v2
	v_mov_b32_e32 v68, v2
	v_mov_b32_e32 v69, v2
	v_mov_b32_e32 v74, v2
	v_mov_b32_e32 v75, v2
	v_mov_b32_e32 v76, v2
	v_mov_b32_e32 v77, v2
	v_mov_b32_e32 v6, v2
	v_mov_b32_e32 v7, v2
	v_mov_b32_e32 v8, v2
	v_mov_b32_e32 v9, v2
	v_mov_b32_e32 v14, v2
	v_mov_b32_e32 v15, v2
	v_mov_b32_e32 v16, v2
	v_mov_b32_e32 v17, v2
	v_mov_b32_e32 v22, v2
	v_mov_b32_e32 v23, v2
	v_mov_b32_e32 v24, v2
	v_mov_b32_e32 v25, v2
	v_mov_b32_e32 v30, v2
	v_mov_b32_e32 v31, v2
	v_mov_b32_e32 v32, v2
	v_mov_b32_e32 v33, v2
	v_mov_b32_e32 v46, v2
	v_mov_b32_e32 v47, v2
	v_mov_b32_e32 v48, v2
	v_mov_b32_e32 v49, v2
	v_mov_b32_e32 v54, v2
	v_mov_b32_e32 v55, v2
	v_mov_b32_e32 v56, v2
	v_mov_b32_e32 v57, v2
	v_mov_b32_e32 v70, v2
	v_mov_b32_e32 v71, v2
	v_mov_b32_e32 v72, v2
	v_mov_b32_e32 v73, v2
	v_mov_b32_e32 v78, v2
	v_mov_b32_e32 v79, v2
	v_mov_b32_e32 v80, v2
	v_mov_b32_e32 v81, v2
	v_mov_b32_e32 v82, v2
	v_mov_b32_e32 v83, v2
	v_mov_b32_e32 v84, v2
	v_mov_b32_e32 v85, v2
	v_mov_b32_e32 v90, v2
	v_mov_b32_e32 v91, v2
	v_mov_b32_e32 v92, v2
	v_mov_b32_e32 v93, v2
	v_mov_b32_e32 v98, v2
	v_mov_b32_e32 v99, v2
	v_mov_b32_e32 v100, v2
	v_mov_b32_e32 v101, v2
	v_mov_b32_e32 v106, v2
	v_mov_b32_e32 v107, v2
	v_mov_b32_e32 v108, v2
	v_mov_b32_e32 v109, v2
	v_mov_b32_e32 v114, v2
	v_mov_b32_e32 v115, v2
	v_mov_b32_e32 v116, v2
	v_mov_b32_e32 v117, v2
	v_mov_b32_e32 v122, v2
	v_mov_b32_e32 v123, v2
	v_mov_b32_e32 v124, v2
	v_mov_b32_e32 v125, v2
	v_mov_b32_e32 v130, v2
	v_mov_b32_e32 v131, v2
	v_mov_b32_e32 v132, v2
	v_mov_b32_e32 v133, v2
	v_mov_b32_e32 v138, v2
	v_mov_b32_e32 v139, v2
	v_mov_b32_e32 v140, v2
	v_mov_b32_e32 v141, v2
	v_mov_b32_e32 v86, v2
	v_mov_b32_e32 v87, v2
	v_mov_b32_e32 v88, v2
	v_mov_b32_e32 v89, v2
	v_mov_b32_e32 v94, v2
	v_mov_b32_e32 v95, v2
	v_mov_b32_e32 v96, v2
	v_mov_b32_e32 v97, v2
	v_mov_b32_e32 v102, v2
	v_mov_b32_e32 v103, v2
	v_mov_b32_e32 v104, v2
	v_mov_b32_e32 v105, v2
	v_mov_b32_e32 v110, v2
	v_mov_b32_e32 v111, v2
	v_mov_b32_e32 v112, v2
	v_mov_b32_e32 v113, v2
	v_mov_b32_e32 v118, v2
	v_mov_b32_e32 v119, v2
	v_mov_b32_e32 v120, v2
	v_mov_b32_e32 v121, v2
	v_mov_b32_e32 v126, v2
	v_mov_b32_e32 v127, v2
	v_mov_b32_e32 v128, v2
	v_mov_b32_e32 v129, v2
	v_mov_b32_e32 v134, v2
	v_mov_b32_e32 v135, v2
	v_mov_b32_e32 v136, v2
	v_mov_b32_e32 v137, v2
	v_mov_b32_e32 v142, v2
	v_mov_b32_e32 v143, v2
	v_mov_b32_e32 v144, v2
	v_mov_b32_e32 v145, v2
	.p2alignl 6, 3212836864

.LBB0_590:
	v_mov_b32_e32 v141, 0
	s_andn2_b64 vcc, exec, s[8:9]
	v_mov_b32_e32 v140, v141
	v_mov_b32_e32 v139, v141
	v_mov_b32_e32 v138, v141
	v_mov_b32_e32 v145, v141
	v_mov_b32_e32 v144, v141
	v_mov_b32_e32 v143, v141
	v_mov_b32_e32 v142, v141
	v_mov_b32_e32 v129, v141
	v_mov_b32_e32 v128, v141
	s_waitcnt vmcnt(0)
	v_mov_b32_e32 v127, v141
	v_mov_b32_e32 v126, v141
	v_mov_b32_e32 v125, v141
	v_mov_b32_e32 v124, v141
	v_mov_b32_e32 v123, v141
	v_mov_b32_e32 v122, v141
	v_mov_b32_e32 v113, v141
	v_mov_b32_e32 v112, v141
	v_mov_b32_e32 v111, v141
	v_mov_b32_e32 v110, v141
	v_mov_b32_e32 v109, v141
	v_mov_b32_e32 v108, v141
	v_mov_b32_e32 v107, v141
	v_mov_b32_e32 v106, v141
	v_mov_b32_e32 v89, v141
	v_mov_b32_e32 v88, v141
	v_mov_b32_e32 v87, v141
	v_mov_b32_e32 v86, v141
	v_mov_b32_e32 v85, v141
	v_mov_b32_e32 v84, v141
	v_mov_b32_e32 v83, v141
	v_mov_b32_e32 v82, v141
	v_mov_b32_e32 v137, v141
	v_mov_b32_e32 v136, v141
	v_mov_b32_e32 v135, v141
	v_mov_b32_e32 v134, v141
	v_mov_b32_e32 v133, v141
	v_mov_b32_e32 v132, v141
	v_mov_b32_e32 v131, v141
	v_mov_b32_e32 v130, v141
	v_mov_b32_e32 v121, v141
	v_mov_b32_e32 v120, v141
	v_mov_b32_e32 v119, v141
	v_mov_b32_e32 v118, v141
	v_mov_b32_e32 v117, v141
	v_mov_b32_e32 v116, v141
	v_mov_b32_e32 v115, v141
	v_mov_b32_e32 v114, v141
	v_mov_b32_e32 v105, v141
	v_mov_b32_e32 v104, v141
	v_mov_b32_e32 v103, v141
	v_mov_b32_e32 v102, v141
	v_mov_b32_e32 v101, v141
	v_mov_b32_e32 v100, v141
	v_mov_b32_e32 v99, v141
	v_mov_b32_e32 v98, v141
	v_mov_b32_e32 v81, v141
	v_mov_b32_e32 v80, v141
	v_mov_b32_e32 v79, v141
	v_mov_b32_e32 v78, v141
	v_mov_b32_e32 v77, v141
	v_mov_b32_e32 v76, v141
	v_mov_b32_e32 v75, v141
	v_mov_b32_e32 v74, v141
	v_mov_b32_e32 v65, v141
	v_mov_b32_e32 v64, v141
	v_mov_b32_e32 v63, v141
	v_mov_b32_e32 v62, v141
	v_mov_b32_e32 v61, v141
	v_mov_b32_e32 v60, v141
	v_mov_b32_e32 v59, v141
	v_mov_b32_e32 v58, v141
	v_mov_b32_e32 v49, v141
	v_mov_b32_e32 v48, v141
	v_mov_b32_e32 v47, v141
	v_mov_b32_e32 v46, v141
	v_mov_b32_e32 v45, v141
	v_mov_b32_e32 v44, v141
	v_mov_b32_e32 v43, v141
	v_mov_b32_e32 v42, v141
	v_mov_b32_e32 v33, v141
	v_mov_b32_e32 v32, v141
	v_mov_b32_e32 v31, v141
	v_mov_b32_e32 v30, v141
	v_mov_b32_e32 v29, v141
	v_mov_b32_e32 v28, v141
	v_mov_b32_e32 v27, v141
	v_mov_b32_e32 v26, v141
	v_mov_b32_e32 v17, v141
	v_mov_b32_e32 v16, v141
	v_mov_b32_e32 v15, v141
	v_mov_b32_e32 v14, v141
	v_mov_b32_e32 v13, v141
	v_mov_b32_e32 v12, v141
	v_mov_b32_e32 v11, v141
	v_mov_b32_e32 v10, v141
	v_mov_b32_e32 v57, v141
	v_mov_b32_e32 v56, v141
	v_mov_b32_e32 v55, v141
	v_mov_b32_e32 v54, v141
	v_mov_b32_e32 v53, v141
	v_mov_b32_e32 v52, v141
	v_mov_b32_e32 v51, v141
	v_mov_b32_e32 v50, v141
	v_mov_b32_e32 v41, v141
	v_mov_b32_e32 v40, v141
	v_mov_b32_e32 v39, v141
	v_mov_b32_e32 v38, v141
	v_mov_b32_e32 v37, v141
	v_mov_b32_e32 v36, v141
	v_mov_b32_e32 v35, v141
	v_mov_b32_e32 v34, v141
	v_mov_b32_e32 v25, v141
	v_mov_b32_e32 v24, v141
	v_mov_b32_e32 v23, v141
	v_mov_b32_e32 v22, v141
	v_mov_b32_e32 v21, v141
	v_mov_b32_e32 v20, v141
	v_mov_b32_e32 v19, v141
	v_mov_b32_e32 v18, v141
	v_mov_b32_e32 v9, v141
	v_mov_b32_e32 v8, v141
	v_mov_b32_e32 v7, v141
	v_mov_b32_e32 v6, v141
	v_mov_b32_e32 v5, v141
	v_mov_b32_e32 v4, v141
	s_waitcnt lgkmcnt(0)
	v_mov_b32_e32 v3, v141
	v_mov_b32_e32 v2, v141
	s_cbranch_vccnz .LBB0_593
	s_add_u32 s49, s10, 0x100
	s_addc_u32 s50, s11, 0
	s_add_u32 s10, s12, 0xc000
	v_mov_b32_e32 v2, 0
	s_addc_u32 s11, s13, 0
	s_mov_b32 s12, 0
	v_mov_b32_e32 v3, v2
	v_mov_b32_e32 v4, v2
	v_mov_b32_e32 v5, v2
	v_mov_b32_e32 v6, v2
	v_mov_b32_e32 v7, v2
	v_mov_b32_e32 v8, v2
	v_mov_b32_e32 v9, v2
	v_mov_b32_e32 v18, v2
	v_mov_b32_e32 v19, v2
	v_mov_b32_e32 v20, v2
	v_mov_b32_e32 v21, v2
	v_mov_b32_e32 v22, v2
	v_mov_b32_e32 v23, v2
	v_mov_b32_e32 v24, v2
	v_mov_b32_e32 v25, v2
	v_mov_b32_e32 v34, v2
	v_mov_b32_e32 v35, v2
	v_mov_b32_e32 v36, v2
	v_mov_b32_e32 v37, v2
	v_mov_b32_e32 v38, v2
	v_mov_b32_e32 v39, v2
	v_mov_b32_e32 v40, v2
	v_mov_b32_e32 v41, v2
	v_mov_b32_e32 v50, v2
	v_mov_b32_e32 v51, v2
	v_mov_b32_e32 v52, v2
	v_mov_b32_e32 v53, v2
	v_mov_b32_e32 v54, v2
	v_mov_b32_e32 v55, v2
	v_mov_b32_e32 v56, v2
	v_mov_b32_e32 v57, v2
	v_mov_b32_e32 v10, v2
	v_mov_b32_e32 v11, v2
	v_mov_b32_e32 v12, v2
	v_mov_b32_e32 v13, v2
	v_mov_b32_e32 v14, v2
	v_mov_b32_e32 v15, v2
	v_mov_b32_e32 v16, v2
	v_mov_b32_e32 v17, v2
	v_mov_b32_e32 v26, v2
	v_mov_b32_e32 v27, v2
	v_mov_b32_e32 v28, v2
	v_mov_b32_e32 v29, v2
	v_mov_b32_e32 v30, v2
	v_mov_b32_e32 v31, v2
	v_mov_b32_e32 v32, v2
	v_mov_b32_e32 v33, v2
	v_mov_b32_e32 v42, v2
	v_mov_b32_e32 v43, v2
	v_mov_b32_e32 v44, v2
	v_mov_b32_e32 v45, v2
	v_mov_b32_e32 v46, v2
	v_mov_b32_e32 v47, v2
	v_mov_b32_e32 v48, v2
	v_mov_b32_e32 v49, v2
	v_mov_b32_e32 v58, v2
	v_mov_b32_e32 v59, v2
	v_mov_b32_e32 v60, v2
	v_mov_b32_e32 v61, v2
	v_mov_b32_e32 v62, v2
	v_mov_b32_e32 v63, v2
	v_mov_b32_e32 v64, v2
	v_mov_b32_e32 v65, v2
	v_mov_b32_e32 v74, v2
	v_mov_b32_e32 v75, v2
	v_mov_b32_e32 v76, v2
	v_mov_b32_e32 v77, v2
	v_mov_b32_e32 v78, v2
	v_mov_b32_e32 v79, v2
	v_mov_b32_e32 v80, v2
	v_mov_b32_e32 v81, v2
	v_mov_b32_e32 v98, v2
	v_mov_b32_e32 v99, v2
	v_mov_b32_e32 v100, v2
	v_mov_b32_e32 v101, v2
	v_mov_b32_e32 v102, v2
	v_mov_b32_e32 v103, v2
	v_mov_b32_e32 v104, v2
	v_mov_b32_e32 v105, v2
	v_mov_b32_e32 v114, v2
	v_mov_b32_e32 v115, v2
	v_mov_b32_e32 v116, v2
	v_mov_b32_e32 v117, v2
	v_mov_b32_e32 v118, v2
	v_mov_b32_e32 v119, v2
	v_mov_b32_e32 v120, v2
	v_mov_b32_e32 v121, v2
	v_mov_b32_e32 v130, v2
	v_mov_b32_e32 v131, v2
	v_mov_b32_e32 v132, v2
	v_mov_b32_e32 v133, v2
	v_mov_b32_e32 v134, v2
	v_mov_b32_e32 v135, v2
	v_mov_b32_e32 v136, v2
	v_mov_b32_e32 v137, v2
	v_mov_b32_e32 v82, v2
	v_mov_b32_e32 v83, v2
	v_mov_b32_e32 v84, v2
	v_mov_b32_e32 v85, v2
	v_mov_b32_e32 v86, v2
	v_mov_b32_e32 v87, v2
	v_mov_b32_e32 v88, v2
	v_mov_b32_e32 v89, v2
	v_mov_b32_e32 v106, v2
	v_mov_b32_e32 v107, v2
	v_mov_b32_e32 v108, v2
	v_mov_b32_e32 v109, v2
	v_mov_b32_e32 v110, v2
	v_mov_b32_e32 v111, v2
	v_mov_b32_e32 v112, v2
	v_mov_b32_e32 v113, v2
	v_mov_b32_e32 v122, v2
	v_mov_b32_e32 v123, v2
	v_mov_b32_e32 v124, v2
	v_mov_b32_e32 v125, v2
	v_mov_b32_e32 v126, v2
	v_mov_b32_e32 v127, v2
	v_mov_b32_e32 v128, v2
	v_mov_b32_e32 v129, v2
	v_mov_b32_e32 v142, v2
	v_mov_b32_e32 v143, v2
	v_mov_b32_e32 v144, v2
	v_mov_b32_e32 v145, v2
	v_mov_b32_e32 v138, v2
	v_mov_b32_e32 v139, v2
	v_mov_b32_e32 v140, v2
	v_mov_b32_e32 v141, v2
	.p2alignl 6, 3212836864

.LBB0_797:
	s_ashr_i32 s15, s14, 31
	s_lshl_b64 s[16:17], s[14:15], 19
	s_add_u32 s16, s64, s16
	s_addc_u32 s17, s65, s17
	s_ashr_i32 s13, s12, 31
	s_lshl_b64 s[18:19], s[12:13], 19
	s_add_u32 s18, s31, s18
	v_mov_b32_e32 v145, 0
	s_addc_u32 s19, s34, s19
	s_andn2_b64 vcc, exec, s[8:9]
	v_mov_b32_e32 v144, v145
	v_mov_b32_e32 v143, v145
	v_mov_b32_e32 v142, v145
	v_mov_b32_e32 v137, v145
	v_mov_b32_e32 v136, v145
	v_mov_b32_e32 v135, v145
	v_mov_b32_e32 v134, v145
	v_mov_b32_e32 v129, v145
	v_mov_b32_e32 v128, v145
	s_waitcnt vmcnt(0)
	v_mov_b32_e32 v127, v145
	v_mov_b32_e32 v126, v145
	v_mov_b32_e32 v121, v145
	v_mov_b32_e32 v120, v145
	v_mov_b32_e32 v119, v145
	v_mov_b32_e32 v118, v145
	v_mov_b32_e32 v113, v145
	v_mov_b32_e32 v112, v145
	v_mov_b32_e32 v111, v145
	v_mov_b32_e32 v110, v145
	v_mov_b32_e32 v105, v145
	v_mov_b32_e32 v104, v145
	v_mov_b32_e32 v103, v145
	v_mov_b32_e32 v102, v145
	v_mov_b32_e32 v97, v145
	v_mov_b32_e32 v96, v145
	v_mov_b32_e32 v95, v145
	v_mov_b32_e32 v94, v145
	v_mov_b32_e32 v89, v145
	v_mov_b32_e32 v88, v145
	v_mov_b32_e32 v87, v145
	v_mov_b32_e32 v86, v145
	v_mov_b32_e32 v141, v145
	v_mov_b32_e32 v140, v145
	v_mov_b32_e32 v139, v145
	v_mov_b32_e32 v138, v145
	v_mov_b32_e32 v133, v145
	v_mov_b32_e32 v132, v145
	v_mov_b32_e32 v131, v145
	v_mov_b32_e32 v130, v145
	v_mov_b32_e32 v125, v145
	v_mov_b32_e32 v124, v145
	v_mov_b32_e32 v123, v145
	v_mov_b32_e32 v122, v145
	v_mov_b32_e32 v117, v145
	v_mov_b32_e32 v116, v145
	v_mov_b32_e32 v115, v145
	v_mov_b32_e32 v114, v145
	v_mov_b32_e32 v109, v145
	v_mov_b32_e32 v108, v145
	v_mov_b32_e32 v107, v145
	v_mov_b32_e32 v106, v145
	v_mov_b32_e32 v101, v145
	v_mov_b32_e32 v100, v145
	v_mov_b32_e32 v99, v145
	v_mov_b32_e32 v98, v145
	v_mov_b32_e32 v93, v145
	v_mov_b32_e32 v92, v145
	v_mov_b32_e32 v91, v145
	v_mov_b32_e32 v90, v145
	v_mov_b32_e32 v85, v145
	v_mov_b32_e32 v84, v145
	v_mov_b32_e32 v83, v145
	v_mov_b32_e32 v82, v145
	v_mov_b32_e32 v81, v145
	v_mov_b32_e32 v80, v145
	v_mov_b32_e32 v79, v145
	v_mov_b32_e32 v78, v145
	v_mov_b32_e32 v73, v145
	v_mov_b32_e32 v72, v145
	v_mov_b32_e32 v71, v145
	v_mov_b32_e32 v70, v145
	v_mov_b32_e32 v65, v145
	v_mov_b32_e32 v64, v145
	v_mov_b32_e32 v63, v145
	v_mov_b32_e32 v62, v145
	v_mov_b32_e32 v57, v145
	v_mov_b32_e32 v56, v145
	v_mov_b32_e32 v55, v145
	v_mov_b32_e32 v54, v145
	v_mov_b32_e32 v41, v145
	v_mov_b32_e32 v40, v145
	v_mov_b32_e32 v39, v145
	v_mov_b32_e32 v38, v145
	v_mov_b32_e32 v29, v145
	v_mov_b32_e32 v28, v145
	v_mov_b32_e32 v27, v145
	v_mov_b32_e32 v26, v145
	v_mov_b32_e32 v17, v145
	v_mov_b32_e32 v16, v145
	v_mov_b32_e32 v15, v145
	v_mov_b32_e32 v14, v145
	v_mov_b32_e32 v9, v145
	v_mov_b32_e32 v8, v145
	v_mov_b32_e32 v7, v145
	v_mov_b32_e32 v6, v145
	v_mov_b32_e32 v77, v145
	v_mov_b32_e32 v76, v145
	v_mov_b32_e32 v75, v145
	v_mov_b32_e32 v74, v145
	v_mov_b32_e32 v69, v145
	v_mov_b32_e32 v68, v145
	v_mov_b32_e32 v67, v145
	v_mov_b32_e32 v66, v145
	v_mov_b32_e32 v61, v145
	v_mov_b32_e32 v60, v145
	v_mov_b32_e32 v59, v145
	v_mov_b32_e32 v58, v145
	v_mov_b32_e32 v53, v145
	v_mov_b32_e32 v52, v145
	v_mov_b32_e32 v51, v145
	v_mov_b32_e32 v50, v145
	v_mov_b32_e32 v33, v145
	v_mov_b32_e32 v32, v145
	v_mov_b32_e32 v31, v145
	v_mov_b32_e32 v30, v145
	v_mov_b32_e32 v21, v145
	v_mov_b32_e32 v20, v145
	v_mov_b32_e32 v19, v145
	v_mov_b32_e32 v18, v145
	v_mov_b32_e32 v13, v145
	v_mov_b32_e32 v12, v145
	v_mov_b32_e32 v11, v145
	v_mov_b32_e32 v10, v145
	v_mov_b32_e32 v5, v145
	v_mov_b32_e32 v4, v145
	v_mov_b32_e32 v3, v145
	v_mov_b32_e32 v2, v145
	s_cbranch_vccnz .LBB0_800
	v_mov_b64_e32 v[2:3], 0x600
	v_cmp_lt_i64_e32 vcc, s[28:29], v[2:3]
	s_and_b64 s[28:29], vcc, exec
	s_cselect_b32 s13, s17, s25
	s_cselect_b32 s15, s16, s24
	s_cselect_b32 s21, s19, s27
	s_cselect_b32 s39, s18, s26
	s_add_u32 s24, s24, 0x40080
	s_addc_u32 s25, s25, 0
	s_add_u32 s55, s26, 0x100
	v_mov_b32_e32 v2, 0
	s_addc_u32 s56, s27, 0
	s_mov_b32 s26, 0
	v_mov_b32_e32 v3, v2
	v_mov_b32_e32 v4, v2
	v_mov_b32_e32 v5, v2
	v_mov_b32_e32 v10, v2
	v_mov_b32_e32 v11, v2
	v_mov_b32_e32 v12, v2
	v_mov_b32_e32 v13, v2
	v_mov_b32_e32 v18, v2
	v_mov_b32_e32 v19, v2
	v_mov_b32_e32 v20, v2
	v_mov_b32_e32 v21, v2
	v_mov_b32_e32 v30, v2
	v_mov_b32_e32 v31, v2
	v_mov_b32_e32 v32, v2
	v_mov_b32_e32 v33, v2
	v_mov_b32_e32 v50, v2
	v_mov_b32_e32 v51, v2
	v_mov_b32_e32 v52, v2
	v_mov_b32_e32 v53, v2
	v_mov_b32_e32 v58, v2
	v_mov_b32_e32 v59, v2
	v_mov_b32_e32 v60, v2
	v_mov_b32_e32 v61, v2
	v_mov_b32_e32 v66, v2
	v_mov_b32_e32 v67, v2
	v_mov_b32_e32 v68, v2
	v_mov_b32_e32 v69, v2
	v_mov_b32_e32 v74, v2
	v_mov_b32_e32 v75, v2
	v_mov_b32_e32 v76, v2
	v_mov_b32_e32 v77, v2
	v_mov_b32_e32 v6, v2
	v_mov_b32_e32 v7, v2
	v_mov_b32_e32 v8, v2
	v_mov_b32_e32 v9, v2
	v_mov_b32_e32 v14, v2
	v_mov_b32_e32 v15, v2
	v_mov_b32_e32 v16, v2
	v_mov_b32_e32 v17, v2
	v_mov_b32_e32 v26, v2
	v_mov_b32_e32 v27, v2
	v_mov_b32_e32 v28, v2
	v_mov_b32_e32 v29, v2
	v_mov_b32_e32 v38, v2
	v_mov_b32_e32 v39, v2
	v_mov_b32_e32 v40, v2
	v_mov_b32_e32 v41, v2
	v_mov_b32_e32 v54, v2
	v_mov_b32_e32 v55, v2
	v_mov_b32_e32 v56, v2
	v_mov_b32_e32 v57, v2
	v_mov_b32_e32 v62, v2
	v_mov_b32_e32 v63, v2
	v_mov_b32_e32 v64, v2
	v_mov_b32_e32 v65, v2
	v_mov_b32_e32 v70, v2
	v_mov_b32_e32 v71, v2
	v_mov_b32_e32 v72, v2
	v_mov_b32_e32 v73, v2
	v_mov_b32_e32 v78, v2
	v_mov_b32_e32 v79, v2
	v_mov_b32_e32 v80, v2
	v_mov_b32_e32 v81, v2
	v_mov_b32_e32 v82, v2
	v_mov_b32_e32 v83, v2
	v_mov_b32_e32 v84, v2
	v_mov_b32_e32 v85, v2
	v_mov_b32_e32 v90, v2
	v_mov_b32_e32 v91, v2
	v_mov_b32_e32 v92, v2
	v_mov_b32_e32 v93, v2
	v_mov_b32_e32 v98, v2
	v_mov_b32_e32 v99, v2
	v_mov_b32_e32 v100, v2
	v_mov_b32_e32 v101, v2
	v_mov_b32_e32 v106, v2
	v_mov_b32_e32 v107, v2
	v_mov_b32_e32 v108, v2
	v_mov_b32_e32 v109, v2
	v_mov_b32_e32 v114, v2
	v_mov_b32_e32 v115, v2
	v_mov_b32_e32 v116, v2
	v_mov_b32_e32 v117, v2
	v_mov_b32_e32 v122, v2
	v_mov_b32_e32 v123, v2
	v_mov_b32_e32 v124, v2
	v_mov_b32_e32 v125, v2
	v_mov_b32_e32 v130, v2
	v_mov_b32_e32 v131, v2
	v_mov_b32_e32 v132, v2
	v_mov_b32_e32 v133, v2
	v_mov_b32_e32 v138, v2
	v_mov_b32_e32 v139, v2
	v_mov_b32_e32 v140, v2
	v_mov_b32_e32 v141, v2
	v_mov_b32_e32 v86, v2
	v_mov_b32_e32 v87, v2
	v_mov_b32_e32 v88, v2
	v_mov_b32_e32 v89, v2
	v_mov_b32_e32 v94, v2
	v_mov_b32_e32 v95, v2
	v_mov_b32_e32 v96, v2
	v_mov_b32_e32 v97, v2
	v_mov_b32_e32 v102, v2
	v_mov_b32_e32 v103, v2
	v_mov_b32_e32 v104, v2
	v_mov_b32_e32 v105, v2
	v_mov_b32_e32 v110, v2
	v_mov_b32_e32 v111, v2
	v_mov_b32_e32 v112, v2
	v_mov_b32_e32 v113, v2
	v_mov_b32_e32 v118, v2
	v_mov_b32_e32 v119, v2
	v_mov_b32_e32 v120, v2
	v_mov_b32_e32 v121, v2
	v_mov_b32_e32 v126, v2
	v_mov_b32_e32 v127, v2
	v_mov_b32_e32 v128, v2
	v_mov_b32_e32 v129, v2
	v_mov_b32_e32 v134, v2
	v_mov_b32_e32 v135, v2
	v_mov_b32_e32 v136, v2
	v_mov_b32_e32 v137, v2
	v_mov_b32_e32 v142, v2
	v_mov_b32_e32 v143, v2
	v_mov_b32_e32 v144, v2
	v_mov_b32_e32 v145, v2
	.p2alignl 6, 3212836864

.LBB0_842:
	v_mov_b32_e32 v137, 0
	s_andn2_b64 vcc, exec, s[10:11]
	v_mov_b32_e32 v136, v137
	v_mov_b32_e32 v135, v137
	v_mov_b32_e32 v134, v137
	s_waitcnt vmcnt(0)
	v_mov_b32_e32 v125, v137
	v_mov_b32_e32 v124, v137
	v_mov_b32_e32 v123, v137
	v_mov_b32_e32 v122, v137
	v_mov_b32_e32 v113, v137
	v_mov_b32_e32 v112, v137
	v_mov_b32_e32 v111, v137
	v_mov_b32_e32 v110, v137
	v_mov_b32_e32 v109, v137
	v_mov_b32_e32 v108, v137
	v_mov_b32_e32 v107, v137
	v_mov_b32_e32 v106, v137
	v_mov_b32_e32 v97, v137
	v_mov_b32_e32 v96, v137
	v_mov_b32_e32 v95, v137
	v_mov_b32_e32 v94, v137
	v_mov_b32_e32 v93, v137
	v_mov_b32_e32 v92, v137
	v_mov_b32_e32 v91, v137
	v_mov_b32_e32 v90, v137
	v_mov_b32_e32 v81, v137
	v_mov_b32_e32 v80, v137
	v_mov_b32_e32 v79, v137
	v_mov_b32_e32 v78, v137
	v_mov_b32_e32 v77, v137
	v_mov_b32_e32 v76, v137
	v_mov_b32_e32 v75, v137
	v_mov_b32_e32 v74, v137
	v_mov_b32_e32 v121, v137
	v_mov_b32_e32 v120, v137
	v_mov_b32_e32 v119, v137
	v_mov_b32_e32 v118, v137
	v_mov_b32_e32 v117, v137
	v_mov_b32_e32 v116, v137
	v_mov_b32_e32 v115, v137
	v_mov_b32_e32 v114, v137
	v_mov_b32_e32 v105, v137
	v_mov_b32_e32 v104, v137
	v_mov_b32_e32 v103, v137
	v_mov_b32_e32 v102, v137
	v_mov_b32_e32 v101, v137
	v_mov_b32_e32 v100, v137
	v_mov_b32_e32 v99, v137
	v_mov_b32_e32 v98, v137
	v_mov_b32_e32 v89, v137
	v_mov_b32_e32 v88, v137
	v_mov_b32_e32 v87, v137
	v_mov_b32_e32 v86, v137
	v_mov_b32_e32 v85, v137
	v_mov_b32_e32 v84, v137
	v_mov_b32_e32 v83, v137
	v_mov_b32_e32 v82, v137
	v_mov_b32_e32 v73, v137
	v_mov_b32_e32 v72, v137
	v_mov_b32_e32 v71, v137
	v_mov_b32_e32 v70, v137
	v_mov_b32_e32 v69, v137
	v_mov_b32_e32 v68, v137
	v_mov_b32_e32 v67, v137
	v_mov_b32_e32 v66, v137
	v_mov_b32_e32 v65, v137
	v_mov_b32_e32 v64, v137
	v_mov_b32_e32 v63, v137
	v_mov_b32_e32 v62, v137
	v_mov_b32_e32 v61, v137
	v_mov_b32_e32 v60, v137
	v_mov_b32_e32 v59, v137
	v_mov_b32_e32 v58, v137
	v_mov_b32_e32 v49, v137
	v_mov_b32_e32 v48, v137
	v_mov_b32_e32 v47, v137
	v_mov_b32_e32 v46, v137
	v_mov_b32_e32 v45, v137
	v_mov_b32_e32 v44, v137
	v_mov_b32_e32 v43, v137
	v_mov_b32_e32 v42, v137
	v_mov_b32_e32 v33, v137
	v_mov_b32_e32 v32, v137
	v_mov_b32_e32 v31, v137
	v_mov_b32_e32 v30, v137
	v_mov_b32_e32 v29, v137
	v_mov_b32_e32 v28, v137
	v_mov_b32_e32 v27, v137
	v_mov_b32_e32 v26, v137
	v_mov_b32_e32 v17, v137
	v_mov_b32_e32 v16, v137
	v_mov_b32_e32 v15, v137
	v_mov_b32_e32 v14, v137
	v_mov_b32_e32 v13, v137
	v_mov_b32_e32 v12, v137
	v_mov_b32_e32 v11, v137
	v_mov_b32_e32 v10, v137
	v_mov_b32_e32 v57, v137
	v_mov_b32_e32 v56, v137
	v_mov_b32_e32 v55, v137
	v_mov_b32_e32 v54, v137
	v_mov_b32_e32 v53, v137
	v_mov_b32_e32 v52, v137
	v_mov_b32_e32 v51, v137
	v_mov_b32_e32 v50, v137
	v_mov_b32_e32 v41, v137
	v_mov_b32_e32 v40, v137
	v_mov_b32_e32 v39, v137
	v_mov_b32_e32 v38, v137
	v_mov_b32_e32 v37, v137
	v_mov_b32_e32 v36, v137
	v_mov_b32_e32 v35, v137
	v_mov_b32_e32 v34, v137
	v_mov_b32_e32 v25, v137
	v_mov_b32_e32 v24, v137
	v_mov_b32_e32 v23, v137
	v_mov_b32_e32 v22, v137
	v_mov_b32_e32 v21, v137
	v_mov_b32_e32 v20, v137
	v_mov_b32_e32 v19, v137
	v_mov_b32_e32 v18, v137
	v_mov_b32_e32 v9, v137
	v_mov_b32_e32 v8, v137
	v_mov_b32_e32 v7, v137
	v_mov_b32_e32 v6, v137
	v_mov_b32_e32 v5, v137
	v_mov_b32_e32 v4, v137
	s_waitcnt lgkmcnt(0)
	v_mov_b32_e32 v3, v137
	v_mov_b32_e32 v2, v137
	s_cbranch_vccnz .LBB0_845
	s_add_u32 s51, s12, 0x100
	s_addc_u32 s52, s13, 0
	s_add_u32 s12, s14, 0xc000
	v_mov_b32_e32 v2, 0
	s_addc_u32 s13, s15, 0
	s_mov_b32 s14, 0
	v_mov_b32_e32 v3, v2
	v_mov_b32_e32 v4, v2
	v_mov_b32_e32 v5, v2
	v_mov_b32_e32 v6, v2
	v_mov_b32_e32 v7, v2
	v_mov_b32_e32 v8, v2
	v_mov_b32_e32 v9, v2
	v_mov_b32_e32 v18, v2
	v_mov_b32_e32 v19, v2
	v_mov_b32_e32 v20, v2
	v_mov_b32_e32 v21, v2
	v_mov_b32_e32 v22, v2
	v_mov_b32_e32 v23, v2
	v_mov_b32_e32 v24, v2
	v_mov_b32_e32 v25, v2
	v_mov_b32_e32 v34, v2
	v_mov_b32_e32 v35, v2
	v_mov_b32_e32 v36, v2
	v_mov_b32_e32 v37, v2
	v_mov_b32_e32 v38, v2
	v_mov_b32_e32 v39, v2
	v_mov_b32_e32 v40, v2
	v_mov_b32_e32 v41, v2
	v_mov_b32_e32 v50, v2
	v_mov_b32_e32 v51, v2
	v_mov_b32_e32 v52, v2
	v_mov_b32_e32 v53, v2
	v_mov_b32_e32 v54, v2
	v_mov_b32_e32 v55, v2
	v_mov_b32_e32 v56, v2
	v_mov_b32_e32 v57, v2
	v_mov_b32_e32 v10, v2
	v_mov_b32_e32 v11, v2
	v_mov_b32_e32 v12, v2
	v_mov_b32_e32 v13, v2
	v_mov_b32_e32 v14, v2
	v_mov_b32_e32 v15, v2
	v_mov_b32_e32 v16, v2
	v_mov_b32_e32 v17, v2
	v_mov_b32_e32 v26, v2
	v_mov_b32_e32 v27, v2
	v_mov_b32_e32 v28, v2
	v_mov_b32_e32 v29, v2
	v_mov_b32_e32 v30, v2
	v_mov_b32_e32 v31, v2
	v_mov_b32_e32 v32, v2
	v_mov_b32_e32 v33, v2
	v_mov_b32_e32 v42, v2
	v_mov_b32_e32 v43, v2
	v_mov_b32_e32 v44, v2
	v_mov_b32_e32 v45, v2
	v_mov_b32_e32 v46, v2
	v_mov_b32_e32 v47, v2
	v_mov_b32_e32 v48, v2
	v_mov_b32_e32 v49, v2
	v_mov_b32_e32 v58, v2
	v_mov_b32_e32 v59, v2
	v_mov_b32_e32 v60, v2
	v_mov_b32_e32 v61, v2
	v_mov_b32_e32 v62, v2
	v_mov_b32_e32 v63, v2
	v_mov_b32_e32 v64, v2
	v_mov_b32_e32 v65, v2
	v_mov_b32_e32 v66, v2
	v_mov_b32_e32 v67, v2
	v_mov_b32_e32 v68, v2
	v_mov_b32_e32 v69, v2
	v_mov_b32_e32 v70, v2
	v_mov_b32_e32 v71, v2
	v_mov_b32_e32 v72, v2
	v_mov_b32_e32 v73, v2
	v_mov_b32_e32 v82, v2
	v_mov_b32_e32 v83, v2
	v_mov_b32_e32 v84, v2
	v_mov_b32_e32 v85, v2
	v_mov_b32_e32 v86, v2
	v_mov_b32_e32 v87, v2
	v_mov_b32_e32 v88, v2
	v_mov_b32_e32 v89, v2
	v_mov_b32_e32 v98, v2
	v_mov_b32_e32 v99, v2
	v_mov_b32_e32 v100, v2
	v_mov_b32_e32 v101, v2
	v_mov_b32_e32 v102, v2
	v_mov_b32_e32 v103, v2
	v_mov_b32_e32 v104, v2
	v_mov_b32_e32 v105, v2
	v_mov_b32_e32 v114, v2
	v_mov_b32_e32 v115, v2
	v_mov_b32_e32 v116, v2
	v_mov_b32_e32 v117, v2
	v_mov_b32_e32 v118, v2
	v_mov_b32_e32 v119, v2
	v_mov_b32_e32 v120, v2
	v_mov_b32_e32 v121, v2
	v_mov_b32_e32 v74, v2
	v_mov_b32_e32 v75, v2
	v_mov_b32_e32 v76, v2
	v_mov_b32_e32 v77, v2
	v_mov_b32_e32 v78, v2
	v_mov_b32_e32 v79, v2
	v_mov_b32_e32 v80, v2
	v_mov_b32_e32 v81, v2
	v_mov_b32_e32 v90, v2
	v_mov_b32_e32 v91, v2
	v_mov_b32_e32 v92, v2
	v_mov_b32_e32 v93, v2
	v_mov_b32_e32 v94, v2
	v_mov_b32_e32 v95, v2
	v_mov_b32_e32 v96, v2
	v_mov_b32_e32 v97, v2
	v_mov_b32_e32 v106, v2
	v_mov_b32_e32 v107, v2
	v_mov_b32_e32 v108, v2
	v_mov_b32_e32 v109, v2
	v_mov_b32_e32 v110, v2
	v_mov_b32_e32 v111, v2
	v_mov_b32_e32 v112, v2
	v_mov_b32_e32 v113, v2
	v_mov_b32_e32 v122, v2
	v_mov_b32_e32 v123, v2
	v_mov_b32_e32 v124, v2
	v_mov_b32_e32 v125, v2
	v_mov_b32_e32 v134, v2
	v_mov_b32_e32 v135, v2
	v_mov_b32_e32 v136, v2
	v_mov_b32_e32 v137, v2
	.p2alignl 6, 3212836864

.LBB0_872:
	s_ashr_i32 s5, s4, 31
	s_lshl_b64 s[6:7], s[4:5], 19
	s_add_u32 s6, s64, s6
	s_addc_u32 s7, s65, s7
	s_ashr_i32 s3, s2, 31
	s_lshl_b64 s[8:9], s[2:3], 19
	s_add_u32 s8, s66, s8
	v_mov_b32_e32 v141, 0
	s_addc_u32 s9, s67, s9
	s_andn2_b64 vcc, exec, s[0:1]
	v_mov_b32_e32 v140, v141
	v_mov_b32_e32 v139, v141
	v_mov_b32_e32 v138, v141
	v_mov_b32_e32 v137, v141
	v_mov_b32_e32 v136, v141
	v_mov_b32_e32 v135, v141
	v_mov_b32_e32 v134, v141
	v_mov_b32_e32 v129, v141
	v_mov_b32_e32 v128, v141
	s_waitcnt vmcnt(0)
	v_mov_b32_e32 v127, v141
	v_mov_b32_e32 v126, v141
	v_mov_b32_e32 v121, v141
	v_mov_b32_e32 v120, v141
	v_mov_b32_e32 v119, v141
	v_mov_b32_e32 v118, v141
	v_mov_b32_e32 v113, v141
	v_mov_b32_e32 v112, v141
	v_mov_b32_e32 v111, v141
	v_mov_b32_e32 v110, v141
	v_mov_b32_e32 v97, v141
	v_mov_b32_e32 v96, v141
	v_mov_b32_e32 v95, v141
	v_mov_b32_e32 v94, v141
	v_mov_b32_e32 v81, v141
	v_mov_b32_e32 v80, v141
	v_mov_b32_e32 v79, v141
	v_mov_b32_e32 v78, v141
	v_mov_b32_e32 v73, v141
	v_mov_b32_e32 v72, v141
	v_mov_b32_e32 v71, v141
	v_mov_b32_e32 v70, v141
	v_mov_b32_e32 v145, v141
	v_mov_b32_e32 v144, v141
	v_mov_b32_e32 v143, v141
	v_mov_b32_e32 v142, v141
	v_mov_b32_e32 v133, v141
	v_mov_b32_e32 v132, v141
	v_mov_b32_e32 v131, v141
	v_mov_b32_e32 v130, v141
	v_mov_b32_e32 v125, v141
	v_mov_b32_e32 v124, v141
	v_mov_b32_e32 v123, v141
	v_mov_b32_e32 v122, v141
	v_mov_b32_e32 v117, v141
	v_mov_b32_e32 v116, v141
	v_mov_b32_e32 v115, v141
	v_mov_b32_e32 v114, v141
	v_mov_b32_e32 v109, v141
	v_mov_b32_e32 v108, v141
	v_mov_b32_e32 v107, v141
	v_mov_b32_e32 v106, v141
	v_mov_b32_e32 v93, v141
	v_mov_b32_e32 v92, v141
	v_mov_b32_e32 v91, v141
	v_mov_b32_e32 v90, v141
	v_mov_b32_e32 v77, v141
	v_mov_b32_e32 v76, v141
	v_mov_b32_e32 v75, v141
	v_mov_b32_e32 v74, v141
	v_mov_b32_e32 v69, v141
	v_mov_b32_e32 v68, v141
	v_mov_b32_e32 v67, v141
	v_mov_b32_e32 v66, v141
	v_mov_b32_e32 v65, v141
	v_mov_b32_e32 v64, v141
	v_mov_b32_e32 v63, v141
	v_mov_b32_e32 v62, v141
	v_mov_b32_e32 v57, v141
	v_mov_b32_e32 v56, v141
	v_mov_b32_e32 v55, v141
	v_mov_b32_e32 v54, v141
	v_mov_b32_e32 v49, v141
	v_mov_b32_e32 v48, v141
	v_mov_b32_e32 v47, v141
	v_mov_b32_e32 v46, v141
	v_mov_b32_e32 v41, v141
	v_mov_b32_e32 v40, v141
	v_mov_b32_e32 v39, v141
	v_mov_b32_e32 v38, v141
	v_mov_b32_e32 v33, v141
	v_mov_b32_e32 v32, v141
	v_mov_b32_e32 v31, v141
	v_mov_b32_e32 v30, v141
	v_mov_b32_e32 v25, v141
	v_mov_b32_e32 v24, v141
	v_mov_b32_e32 v23, v141
	v_mov_b32_e32 v22, v141
	v_mov_b32_e32 v17, v141
	v_mov_b32_e32 v16, v141
	v_mov_b32_e32 v15, v141
	v_mov_b32_e32 v14, v141
	v_mov_b32_e32 v9, v141
	v_mov_b32_e32 v8, v141
	v_mov_b32_e32 v7, v141
	v_mov_b32_e32 v6, v141
	v_mov_b32_e32 v61, v141
	v_mov_b32_e32 v60, v141
	v_mov_b32_e32 v59, v141
	v_mov_b32_e32 v58, v141
	v_mov_b32_e32 v53, v141
	v_mov_b32_e32 v52, v141
	v_mov_b32_e32 v51, v141
	v_mov_b32_e32 v50, v141
	v_mov_b32_e32 v45, v141
	v_mov_b32_e32 v44, v141
	v_mov_b32_e32 v43, v141
	v_mov_b32_e32 v42, v141
	v_mov_b32_e32 v37, v141
	v_mov_b32_e32 v36, v141
	v_mov_b32_e32 v35, v141
	v_mov_b32_e32 v34, v141
	v_mov_b32_e32 v29, v141
	v_mov_b32_e32 v28, v141
	v_mov_b32_e32 v27, v141
	v_mov_b32_e32 v26, v141
	v_mov_b32_e32 v21, v141
	v_mov_b32_e32 v20, v141
	v_mov_b32_e32 v19, v141
	v_mov_b32_e32 v18, v141
	v_mov_b32_e32 v13, v141
	v_mov_b32_e32 v12, v141
	v_mov_b32_e32 v11, v141
	v_mov_b32_e32 v10, v141
	v_mov_b32_e32 v5, v141
	v_mov_b32_e32 v4, v141
	v_mov_b32_e32 v3, v141
	v_mov_b32_e32 v2, v141
	s_cbranch_vccnz .LBB0_869
	v_mov_b64_e32 v[2:3], 0xb00
	v_cmp_lt_i64_e32 vcc, s[16:17], v[2:3]
	s_and_b64 s[16:17], vcc, exec
	s_cselect_b32 s3, s7, s13
	s_cselect_b32 s5, s6, s12
	s_cselect_b32 s39, s9, s15
	s_cselect_b32 s40, s8, s14
	s_add_u32 s12, s12, 0x40080
	s_addc_u32 s13, s13, 0
	s_add_u32 s41, s14, 0x100
	v_mov_b32_e32 v2, 0
	s_addc_u32 s42, s15, 0
	s_mov_b32 s14, 0
	v_mov_b32_e32 v3, v2
	v_mov_b32_e32 v4, v2
	v_mov_b32_e32 v5, v2
	v_mov_b32_e32 v10, v2
	v_mov_b32_e32 v11, v2
	v_mov_b32_e32 v12, v2
	v_mov_b32_e32 v13, v2
	v_mov_b32_e32 v18, v2
	v_mov_b32_e32 v19, v2
	v_mov_b32_e32 v20, v2
	v_mov_b32_e32 v21, v2
	v_mov_b32_e32 v26, v2
	v_mov_b32_e32 v27, v2
	v_mov_b32_e32 v28, v2
	v_mov_b32_e32 v29, v2
	v_mov_b32_e32 v34, v2
	v_mov_b32_e32 v35, v2
	v_mov_b32_e32 v36, v2
	v_mov_b32_e32 v37, v2
	v_mov_b32_e32 v42, v2
	v_mov_b32_e32 v43, v2
	v_mov_b32_e32 v44, v2
	v_mov_b32_e32 v45, v2
	v_mov_b32_e32 v50, v2
	v_mov_b32_e32 v51, v2
	v_mov_b32_e32 v52, v2
	v_mov_b32_e32 v53, v2
	v_mov_b32_e32 v58, v2
	v_mov_b32_e32 v59, v2
	v_mov_b32_e32 v60, v2
	v_mov_b32_e32 v61, v2
	v_mov_b32_e32 v6, v2
	v_mov_b32_e32 v7, v2
	v_mov_b32_e32 v8, v2
	v_mov_b32_e32 v9, v2
	v_mov_b32_e32 v14, v2
	v_mov_b32_e32 v15, v2
	v_mov_b32_e32 v16, v2
	v_mov_b32_e32 v17, v2
	v_mov_b32_e32 v22, v2
	v_mov_b32_e32 v23, v2
	v_mov_b32_e32 v24, v2
	v_mov_b32_e32 v25, v2
	v_mov_b32_e32 v30, v2
	v_mov_b32_e32 v31, v2
	v_mov_b32_e32 v32, v2
	v_mov_b32_e32 v33, v2
	v_mov_b32_e32 v38, v2
	v_mov_b32_e32 v39, v2
	v_mov_b32_e32 v40, v2
	v_mov_b32_e32 v41, v2
	v_mov_b32_e32 v46, v2
	v_mov_b32_e32 v47, v2
	v_mov_b32_e32 v48, v2
	v_mov_b32_e32 v49, v2
	v_mov_b32_e32 v54, v2
	v_mov_b32_e32 v55, v2
	v_mov_b32_e32 v56, v2
	v_mov_b32_e32 v57, v2
	v_mov_b32_e32 v62, v2
	v_mov_b32_e32 v63, v2
	v_mov_b32_e32 v64, v2
	v_mov_b32_e32 v65, v2
	v_mov_b32_e32 v66, v2
	v_mov_b32_e32 v67, v2
	v_mov_b32_e32 v68, v2
	v_mov_b32_e32 v69, v2
	v_mov_b32_e32 v74, v2
	v_mov_b32_e32 v75, v2
	v_mov_b32_e32 v76, v2
	v_mov_b32_e32 v77, v2
	v_mov_b32_e32 v90, v2
	v_mov_b32_e32 v91, v2
	v_mov_b32_e32 v92, v2
	v_mov_b32_e32 v93, v2
	v_mov_b32_e32 v106, v2
	v_mov_b32_e32 v107, v2
	v_mov_b32_e32 v108, v2
	v_mov_b32_e32 v109, v2
	v_mov_b32_e32 v114, v2
	v_mov_b32_e32 v115, v2
	v_mov_b32_e32 v116, v2
	v_mov_b32_e32 v117, v2
	v_mov_b32_e32 v122, v2
	v_mov_b32_e32 v123, v2
	v_mov_b32_e32 v124, v2
	v_mov_b32_e32 v125, v2
	v_mov_b32_e32 v130, v2
	v_mov_b32_e32 v131, v2
	v_mov_b32_e32 v132, v2
	v_mov_b32_e32 v133, v2
	v_mov_b32_e32 v142, v2
	v_mov_b32_e32 v143, v2
	v_mov_b32_e32 v144, v2
	v_mov_b32_e32 v145, v2
	v_mov_b32_e32 v70, v2
	v_mov_b32_e32 v71, v2
	v_mov_b32_e32 v72, v2
	v_mov_b32_e32 v73, v2
	v_mov_b32_e32 v78, v2
	v_mov_b32_e32 v79, v2
	v_mov_b32_e32 v80, v2
	v_mov_b32_e32 v81, v2
	v_mov_b32_e32 v94, v2
	v_mov_b32_e32 v95, v2
	v_mov_b32_e32 v96, v2
	v_mov_b32_e32 v97, v2
	v_mov_b32_e32 v110, v2
	v_mov_b32_e32 v111, v2
	v_mov_b32_e32 v112, v2
	v_mov_b32_e32 v113, v2
	v_mov_b32_e32 v118, v2
	v_mov_b32_e32 v119, v2
	v_mov_b32_e32 v120, v2
	v_mov_b32_e32 v121, v2
	v_mov_b32_e32 v126, v2
	v_mov_b32_e32 v127, v2
	v_mov_b32_e32 v128, v2
	v_mov_b32_e32 v129, v2
	v_mov_b32_e32 v134, v2
	v_mov_b32_e32 v135, v2
	v_mov_b32_e32 v136, v2
	v_mov_b32_e32 v137, v2
	v_mov_b32_e32 v138, v2
	v_mov_b32_e32 v139, v2
	v_mov_b32_e32 v140, v2
	v_mov_b32_e32 v141, v2
	.p2alignl 6, 3212836864
